# barrier members poll top generation word; GLA pass-3 gate and gain loads hoisted to item start; MoBA epilogue gate loads batched
# speedup vs baseline: 1.0248x; 1.0106x over previous
.LBB0_143:
	global_atomic_add v4, v[192:193], v6, off sc0
	v_cvt_f32_u32_e32 v1, v3
	v_sub_u32_e32 v5, 0, v3
	v_rcp_iflag_f32_e32 v1, v1
	s_nop 0
	v_mul_f32_e32 v1, 0x4f7ffffe, v1
	v_cvt_u32_f32_e32 v1, v1
	v_mul_lo_u32 v5, v5, v1
	v_mul_hi_u32 v5, v1, v5
	v_add_u32_e32 v1, v1, v5
	s_waitcnt vmcnt(0)
	v_mul_hi_u32 v1, v4, v1
	v_mul_lo_u32 v5, v1, v3
	v_sub_u32_e32 v5, v4, v5
	v_add_u32_e32 v7, 1, v1
	v_cmp_ge_u32_e32 vcc, v5, v3
	v_add_u32_e32 v4, 1, v4
	s_nop 0
	v_cndmask_b32_e32 v1, v1, v7, vcc
	v_sub_u32_e32 v7, v5, v3
	v_cndmask_b32_e32 v5, v5, v7, vcc
	v_add_u32_e32 v7, 1, v1
	v_cmp_ge_u32_e32 vcc, v5, v3
	s_nop 1
	v_cndmask_b32_e32 v1, v1, v7, vcc
	v_mul_lo_u32 v5, v3, v1
	v_add_u32_e32 v3, v5, v3
	v_cmp_ne_u32_e32 vcc, v4, v3
	s_and_saveexec_b64 s[8:9], vcc
	s_xor_b64 s[8:9], exec, s[8:9]
	s_cbranch_execz .LBB0_157
	s_waitcnt lgkmcnt(0)
	v_readlane_b32 s98, v249, 20
	v_readlane_b32 s99, v249, 21
	s_nop 4
	global_load_dword v0, v2, s[98:99] sc1
	s_waitcnt vmcnt(0)
	v_cmp_eq_u32_e32 vcc, v0, v1
	s_and_saveexec_b64 s[10:11], vcc
	s_cbranch_execz .LBB0_156
	s_mov_b32 s34, 1
	s_mov_b64 s[12:13], 0
	s_branch .LBB0_147

.LBB0_151:
	global_load_dword v0, v2, s[98:99] sc1
	s_add_i32 s34, s34, 1
	s_mov_b64 s[18:19], -1
	s_waitcnt vmcnt(0)
	v_cmp_ne_u32_e32 vcc, v0, v1
	s_orn2_b64 s[16:17], vcc, exec
	s_branch .LBB0_146

.LBB0_329:
	s_waitcnt lgkmcnt(0)
	s_barrier
	ds_read_b32 v4, v92 offset:53760
	v_add_u32_e32 v16, v93, v128
	s_waitcnt vmcnt(2)
	v_mov_b64_e32 v[24:25], s[4:5]
	v_mov_b32_e32 v1, v2
	v_ashrrev_i32_e32 v17, 31, v16
	s_waitcnt lgkmcnt(0)
	v_div_scale_f32 v5, s[2:3], v4, v4, 1.0
	v_rcp_f32_e32 v7, v5
	s_movk_i32 s2, 0x10c
	v_mad_u64_u32 v[26:27], s[2:3], v93, s2, v[92:93]
	v_fma_f32 v12, -v5, v7, 1.0
	v_fmac_f32_e32 v7, v12, v7
	v_div_scale_f32 v12, vcc, 1.0, v4, 1.0
	v_mul_f32_e32 v13, v12, v7
	v_fma_f32 v15, -v5, v13, v12
	v_fmac_f32_e32 v13, v15, v7
	v_fma_f32 v5, -v5, v13, v12
	v_div_fmas_f32 v5, v5, v7, v13
	v_mad_i64_i32 v[12:13], s[2:3], v16, s93, v[24:25]
	v_lshl_add_u64 v[8:9], s[6:7], 0, v[0:1]
	s_waitcnt vmcnt(1)
	v_lshl_add_u64 v[28:29], v[12:13], 0, v[0:1]
	v_lshlrev_b64 v[12:13], 11, v[16:17]
	s_waitcnt vmcnt(0)
	v_lshl_add_u64 v[32:33], v[8:9], 0, v[12:13]
	v_lshlrev_b32_e32 v12, 3, v3
	v_mov_b32_e32 v13, v2
	v_lshl_add_u64 v[30:31], v[28:29], 0, v[12:13]
	global_load_dwordx2 v[28:29], v[30:31], off offset:1536
	s_mov_b64 s[100:101], 0x1a800
	v_lshl_add_u64 v[174:175], v[30:31], 0, s[100:101]
	global_load_dwordx2 v[160:161], v[30:31], off offset:1568
	global_load_dwordx2 v[162:163], v[30:31], off offset:1600
	global_load_dwordx2 v[164:165], v[30:31], off offset:1632
	global_load_dwordx2 v[166:167], v[174:175], off offset:1536
	global_load_dwordx2 v[168:169], v[174:175], off offset:1568
	global_load_dwordx2 v[170:171], v[174:175], off offset:1600
	global_load_dwordx2 v[172:173], v[174:175], off offset:1632
	v_div_fixup_f32 v4, v5, v4, 1.0
	v_lshl_add_u32 v5, v3, 4, v26
	ds_read_b128 v[20:23], v5 offset:18432
	v_add_u32_e32 v16, 16, v16
	s_waitcnt lgkmcnt(0)
	v_pk_mul_f32 v[20:21], v[4:5], v[20:21] op_sel_hi:[0,1]
	v_pk_mul_f32 v[22:23], v[4:5], v[22:23] op_sel_hi:[0,1]
	s_waitcnt vmcnt(0)
	v_lshlrev_b32_e32 v3, 16, v28
	v_and_b32_e32 v7, 0xffff0000, v28
	v_mul_f32_e32 v15, 0xbfb8aa3b, v3
	v_exp_f32_e32 v34, v15
	v_mul_f32_e32 v15, 0xbfb8aa3b, v7
	v_exp_f32_e32 v35, v15
	s_nop 0
	v_pk_add_f32 v[34:35], v[34:35], 1.0 op_sel_hi:[1,0]
	s_nop 0
	v_div_scale_f32 v15, s[2:3], v35, v35, v7
	v_rcp_f32_e32 v17, v15
	s_nop 0
	v_fma_f32 v19, -v15, v17, 1.0
	v_fmac_f32_e32 v17, v19, v17
	v_div_scale_f32 v19, vcc, v7, v35, v7
	v_mul_f32_e32 v27, v19, v17
	v_fma_f32 v28, -v15, v27, v19
	v_fmac_f32_e32 v27, v28, v17
	v_fma_f32 v15, -v15, v27, v19
	v_div_fmas_f32 v15, v15, v17, v27
	v_div_fixup_f32 v35, v15, v35, v7
	v_div_scale_f32 v7, s[2:3], v34, v34, v3
	v_rcp_f32_e32 v15, v7
	s_nop 0
	v_fma_f32 v17, -v7, v15, 1.0
	v_fmac_f32_e32 v15, v17, v15
	v_div_scale_f32 v17, vcc, v3, v34, v3
	v_mul_f32_e32 v19, v17, v15
	v_fma_f32 v27, -v7, v19, v17
	v_fmac_f32_e32 v19, v27, v15
	v_fma_f32 v7, -v7, v19, v17
	v_div_fmas_f32 v7, v7, v15, v19
	v_div_fixup_f32 v34, v7, v34, v3
	v_lshlrev_b32_e32 v3, 16, v29
	v_and_b32_e32 v7, 0xffff0000, v29
	v_mul_f32_e32 v15, 0xbfb8aa3b, v3
	v_exp_f32_e32 v28, v15
	v_mul_f32_e32 v15, 0xbfb8aa3b, v7
	v_exp_f32_e32 v29, v15
	v_pk_mul_f32 v[20:21], v[20:21], v[34:35]
	v_pk_add_f32 v[28:29], v[28:29], 1.0 op_sel_hi:[1,0]
	s_nop 0
	v_div_scale_f32 v15, s[2:3], v29, v29, v7
	v_rcp_f32_e32 v17, v15
	v_cvt_pk_bf16_f32 v20, v20, v21
	v_fma_f32 v19, -v15, v17, 1.0
	v_fmac_f32_e32 v17, v19, v17
	v_div_scale_f32 v19, vcc, v7, v29, v7
	v_mul_f32_e32 v21, v19, v17
	v_fma_f32 v27, -v15, v21, v19
	v_fmac_f32_e32 v21, v27, v17
	v_fma_f32 v15, -v15, v21, v19
	v_div_fmas_f32 v15, v15, v17, v21
	v_div_fixup_f32 v29, v15, v29, v7
	v_div_scale_f32 v7, s[2:3], v28, v28, v3
	v_rcp_f32_e32 v15, v7
	s_nop 0
	v_fma_f32 v17, -v7, v15, 1.0
	v_fmac_f32_e32 v15, v17, v15
	v_div_scale_f32 v17, vcc, v3, v28, v3
	v_mul_f32_e32 v19, v17, v15
	v_fma_f32 v21, -v7, v19, v17
	v_fmac_f32_e32 v19, v21, v15
	v_fma_f32 v7, -v7, v19, v17
	v_div_fmas_f32 v7, v7, v15, v19
	v_div_fixup_f32 v28, v7, v28, v3
	v_pk_mul_f32 v[22:23], v[22:23], v[28:29]
	v_lshl_add_u64 v[28:29], v[32:33], 0, v[12:13]
	v_mov_b64_e32 v[32:33], v[160:161]
	v_cvt_pk_bf16_f32 v21, v22, v23
	global_store_dwordx2 v[28:29], v[20:21], off
	ds_read_b128 v[20:23], v5 offset:18496
	s_waitcnt lgkmcnt(0)
	v_pk_mul_f32 v[20:21], v[4:5], v[20:21] op_sel_hi:[0,1]
	v_pk_mul_f32 v[22:23], v[4:5], v[22:23] op_sel_hi:[0,1]
	s_nop 0
	v_lshlrev_b32_e32 v3, 16, v32
	v_and_b32_e32 v7, 0xffff0000, v32
	v_mul_f32_e32 v15, 0xbfb8aa3b, v3
	v_exp_f32_e32 v34, v15
	v_mul_f32_e32 v15, 0xbfb8aa3b, v7
	v_exp_f32_e32 v35, v15
	s_nop 0
	v_pk_add_f32 v[34:35], v[34:35], 1.0 op_sel_hi:[1,0]
	s_nop 0
	v_div_scale_f32 v15, s[2:3], v35, v35, v7
	v_rcp_f32_e32 v17, v15
	s_nop 0
	v_fma_f32 v19, -v15, v17, 1.0
	v_fmac_f32_e32 v17, v19, v17
	v_div_scale_f32 v19, vcc, v7, v35, v7
	v_mul_f32_e32 v27, v19, v17
	v_fma_f32 v32, -v15, v27, v19
	v_fmac_f32_e32 v27, v32, v17
	v_fma_f32 v15, -v15, v27, v19
	v_div_fmas_f32 v15, v15, v17, v27
	v_div_fixup_f32 v35, v15, v35, v7
	v_div_scale_f32 v7, s[2:3], v34, v34, v3
	v_rcp_f32_e32 v15, v7
	s_nop 0
	v_fma_f32 v17, -v7, v15, 1.0
	v_fmac_f32_e32 v15, v17, v15
	v_div_scale_f32 v17, vcc, v3, v34, v3
	v_mul_f32_e32 v19, v17, v15
	v_fma_f32 v27, -v7, v19, v17
	v_fmac_f32_e32 v19, v27, v15
	v_fma_f32 v7, -v7, v19, v17
	v_div_fmas_f32 v7, v7, v15, v19
	v_div_fixup_f32 v34, v7, v34, v3
	v_lshlrev_b32_e32 v3, 16, v33
	v_and_b32_e32 v7, 0xffff0000, v33
	v_mul_f32_e32 v15, 0xbfb8aa3b, v3
	v_exp_f32_e32 v32, v15
	v_mul_f32_e32 v15, 0xbfb8aa3b, v7
	v_exp_f32_e32 v33, v15
	v_pk_mul_f32 v[20:21], v[20:21], v[34:35]
	v_pk_add_f32 v[32:33], v[32:33], 1.0 op_sel_hi:[1,0]
	s_nop 0
	v_div_scale_f32 v15, s[2:3], v33, v33, v7
	v_rcp_f32_e32 v17, v15
	v_cvt_pk_bf16_f32 v20, v20, v21
	v_fma_f32 v19, -v15, v17, 1.0
	v_fmac_f32_e32 v17, v19, v17
	v_div_scale_f32 v19, vcc, v7, v33, v7
	v_mul_f32_e32 v21, v19, v17
	v_fma_f32 v27, -v15, v21, v19
	v_fmac_f32_e32 v21, v27, v17
	v_fma_f32 v15, -v15, v21, v19
	v_div_fmas_f32 v15, v15, v17, v21
	v_div_fixup_f32 v33, v15, v33, v7
	v_div_scale_f32 v7, s[2:3], v32, v32, v3
	v_rcp_f32_e32 v15, v7
	s_nop 0
	v_fma_f32 v17, -v7, v15, 1.0
	v_fmac_f32_e32 v15, v17, v15
	v_div_scale_f32 v17, vcc, v3, v32, v3
	v_mul_f32_e32 v19, v17, v15
	v_fma_f32 v21, -v7, v19, v17
	v_fmac_f32_e32 v19, v21, v15
	v_fma_f32 v7, -v7, v19, v17
	v_div_fmas_f32 v7, v7, v15, v19
	v_div_fixup_f32 v32, v7, v32, v3
	v_pk_mul_f32 v[22:23], v[22:23], v[32:33]
	v_mov_b64_e32 v[32:33], v[162:163]
	v_cvt_pk_bf16_f32 v21, v22, v23
	v_mov_b64_e32 v[30:31], v[164:165]
	s_nop 0
	v_lshlrev_b32_e32 v3, 16, v32
	v_and_b32_e32 v7, 0xffff0000, v32
	v_mul_f32_e32 v15, 0xbfb8aa3b, v3
	v_exp_f32_e32 v34, v15
	v_mul_f32_e32 v15, 0xbfb8aa3b, v7
	v_exp_f32_e32 v35, v15
	global_store_dwordx2 v[28:29], v[20:21], off offset:32
	ds_read_b128 v[20:23], v5 offset:18560
	v_pk_add_f32 v[34:35], v[34:35], 1.0 op_sel_hi:[1,0]
	s_nop 0
	v_div_scale_f32 v15, s[2:3], v35, v35, v7
	v_rcp_f32_e32 v17, v15
	s_waitcnt lgkmcnt(0)
	v_pk_mul_f32 v[20:21], v[4:5], v[20:21] op_sel_hi:[0,1]
	v_pk_mul_f32 v[22:23], v[4:5], v[22:23] op_sel_hi:[0,1]
	v_fma_f32 v19, -v15, v17, 1.0
	v_fmac_f32_e32 v17, v19, v17
	v_div_scale_f32 v19, vcc, v7, v35, v7
	v_mul_f32_e32 v27, v19, v17
	v_fma_f32 v32, -v15, v27, v19
	v_fmac_f32_e32 v27, v32, v17
	v_fma_f32 v15, -v15, v27, v19
	v_div_fmas_f32 v15, v15, v17, v27
	v_div_fixup_f32 v35, v15, v35, v7
	v_div_scale_f32 v7, s[2:3], v34, v34, v3
	v_rcp_f32_e32 v15, v7
	s_nop 0
	v_fma_f32 v17, -v7, v15, 1.0
	v_fmac_f32_e32 v15, v17, v15
	v_div_scale_f32 v17, vcc, v3, v34, v3
	v_mul_f32_e32 v19, v17, v15
	v_fma_f32 v27, -v7, v19, v17
	v_fmac_f32_e32 v19, v27, v15
	v_fma_f32 v7, -v7, v19, v17
	v_div_fmas_f32 v7, v7, v15, v19
	v_div_fixup_f32 v34, v7, v34, v3
	v_lshlrev_b32_e32 v3, 16, v33
	v_and_b32_e32 v7, 0xffff0000, v33
	v_mul_f32_e32 v15, 0xbfb8aa3b, v3
	v_exp_f32_e32 v32, v15
	v_mul_f32_e32 v15, 0xbfb8aa3b, v7
	v_exp_f32_e32 v33, v15
	v_pk_mul_f32 v[20:21], v[20:21], v[34:35]
	v_pk_add_f32 v[32:33], v[32:33], 1.0 op_sel_hi:[1,0]
	s_nop 0
	v_div_scale_f32 v15, s[2:3], v33, v33, v7
	v_rcp_f32_e32 v17, v15
	v_cvt_pk_bf16_f32 v20, v20, v21
	v_fma_f32 v19, -v15, v17, 1.0
	v_fmac_f32_e32 v17, v19, v17
	v_div_scale_f32 v19, vcc, v7, v33, v7
	v_mul_f32_e32 v21, v19, v17
	v_fma_f32 v27, -v15, v21, v19
	v_fmac_f32_e32 v21, v27, v17
	v_fma_f32 v15, -v15, v21, v19
	v_div_fmas_f32 v15, v15, v17, v21
	v_div_fixup_f32 v33, v15, v33, v7
	v_div_scale_f32 v7, s[2:3], v32, v32, v3
	v_rcp_f32_e32 v15, v7
	s_nop 0
	v_fma_f32 v17, -v7, v15, 1.0
	v_fmac_f32_e32 v15, v17, v15
	v_div_scale_f32 v17, vcc, v3, v32, v3
	v_mul_f32_e32 v19, v17, v15
	v_fma_f32 v21, -v7, v19, v17
	v_fmac_f32_e32 v19, v21, v15
	v_fma_f32 v7, -v7, v19, v17
	v_div_fmas_f32 v7, v7, v15, v19
	v_div_fixup_f32 v32, v7, v32, v3
	s_nop 0
	v_lshlrev_b32_e32 v3, 16, v30
	v_and_b32_e32 v7, 0xffff0000, v30
	v_mul_f32_e32 v15, 0xbfb8aa3b, v3
	v_pk_mul_f32 v[22:23], v[22:23], v[32:33]
	v_exp_f32_e32 v32, v15
	v_mul_f32_e32 v15, 0xbfb8aa3b, v7
	v_exp_f32_e32 v33, v15
	v_cvt_pk_bf16_f32 v21, v22, v23
	global_store_dwordx2 v[28:29], v[20:21], off offset:64
	ds_read_b128 v[20:23], v5 offset:18624
	v_pk_add_f32 v[32:33], v[32:33], 1.0 op_sel_hi:[1,0]
	s_waitcnt lgkmcnt(0)
	v_pk_mul_f32 v[20:21], v[4:5], v[20:21] op_sel_hi:[0,1]
	v_div_scale_f32 v15, s[2:3], v33, v33, v7
	v_rcp_f32_e32 v17, v15
	v_pk_mul_f32 v[22:23], v[4:5], v[22:23] op_sel_hi:[0,1]
	v_fma_f32 v19, -v15, v17, 1.0
	v_fmac_f32_e32 v17, v19, v17
	v_div_scale_f32 v19, vcc, v7, v33, v7
	v_mul_f32_e32 v27, v19, v17
	v_fma_f32 v30, -v15, v27, v19
	v_fmac_f32_e32 v27, v30, v17
	v_fma_f32 v15, -v15, v27, v19
	v_div_fmas_f32 v15, v15, v17, v27
	v_div_fixup_f32 v33, v15, v33, v7
	v_div_scale_f32 v7, s[2:3], v32, v32, v3
	v_rcp_f32_e32 v15, v7
	s_nop 0
	v_fma_f32 v17, -v7, v15, 1.0
	v_fmac_f32_e32 v15, v17, v15
	v_div_scale_f32 v17, vcc, v3, v32, v3
	v_mul_f32_e32 v19, v17, v15
	v_fma_f32 v27, -v7, v19, v17
	v_fmac_f32_e32 v19, v27, v15
	v_fma_f32 v7, -v7, v19, v17
	v_div_fmas_f32 v7, v7, v15, v19
	v_div_fixup_f32 v32, v7, v32, v3
	v_lshlrev_b32_e32 v3, 16, v31
	v_and_b32_e32 v7, 0xffff0000, v31
	v_mul_f32_e32 v15, 0xbfb8aa3b, v3
	v_mul_f32_e32 v4, 0xbfb8aa3b, v7
	v_exp_f32_e32 v30, v15
	v_exp_f32_e32 v31, v4
	v_pk_mul_f32 v[20:21], v[20:21], v[32:33]
	v_pk_add_f32 v[30:31], v[30:31], 1.0 op_sel_hi:[1,0]
	s_nop 0
	v_div_scale_f32 v4, s[2:3], v31, v31, v7
	v_rcp_f32_e32 v15, v4
	v_cvt_pk_bf16_f32 v20, v20, v21
	v_fma_f32 v17, -v4, v15, 1.0
	v_fmac_f32_e32 v15, v17, v15
	v_div_scale_f32 v17, vcc, v7, v31, v7
	v_mul_f32_e32 v19, v17, v15
	v_fma_f32 v21, -v4, v19, v17
	v_fmac_f32_e32 v19, v21, v15
	v_fma_f32 v4, -v4, v19, v17
	v_div_fmas_f32 v4, v4, v15, v19
	v_div_fixup_f32 v31, v4, v31, v7
	v_div_scale_f32 v4, s[2:3], v30, v30, v3
	v_rcp_f32_e32 v7, v4
	s_movk_i32 s2, 0xfef4
	v_fma_f32 v15, -v4, v7, 1.0
	v_fmac_f32_e32 v7, v15, v7
	v_div_scale_f32 v15, vcc, v3, v30, v3
	v_mul_f32_e32 v17, v15, v7
	v_fma_f32 v19, -v4, v17, v15
	v_fmac_f32_e32 v17, v19, v7
	v_fma_f32 v4, -v4, v17, v15
	v_div_fmas_f32 v4, v4, v7, v17
	v_div_fixup_f32 v30, v4, v30, v3
	v_pk_mul_f32 v[22:23], v[22:23], v[30:31]
	s_nop 0
	v_cvt_pk_bf16_f32 v21, v22, v23
	global_store_dwordx2 v[28:29], v[20:21], off offset:96
	v_mad_u64_u32 v[20:21], s[2:3], v93, s2, v[26:27]
	ds_read_b32 v3, v20 offset:53824
	v_mad_i64_i32 v[20:21], s[2:3], v16, s93, v[24:25]
	v_lshl_add_u64 v[0:1], v[20:21], 0, v[0:1]
	ds_read_b128 v[20:23], v5 offset:22784
	s_waitcnt lgkmcnt(1)
	v_div_scale_f32 v4, s[2:3], v3, v3, 1.0
	v_rcp_f32_e32 v7, v4
	s_nop 0
	v_fma_f32 v15, -v4, v7, 1.0
	v_fmac_f32_e32 v7, v15, v7
	v_div_scale_f32 v15, vcc, 1.0, v3, 1.0
	v_mul_f32_e32 v17, v15, v7
	v_fma_f32 v19, -v4, v17, v15
	v_fmac_f32_e32 v17, v19, v7
	v_fma_f32 v4, -v4, v17, v15
	v_div_fmas_f32 v4, v4, v7, v17
	v_ashrrev_i32_e32 v17, 31, v16
	v_lshlrev_b64 v[16:17], 11, v[16:17]
	v_lshl_add_u64 v[16:17], v[8:9], 0, v[16:17]
	v_lshl_add_u64 v[8:9], v[0:1], 0, v[12:13]
	v_mov_b64_e32 v[0:1], v[166:167]
	v_div_fixup_f32 v4, v4, v3, 1.0
	s_waitcnt lgkmcnt(0)
	v_pk_mul_f32 v[20:21], v[4:5], v[20:21] op_sel_hi:[0,1]
	v_pk_mul_f32 v[22:23], v[4:5], v[22:23] op_sel_hi:[0,1]
	s_nop 0
	v_lshlrev_b32_e32 v3, 16, v0
	v_and_b32_e32 v0, 0xffff0000, v0
	v_mul_f32_e32 v7, 0xbfb8aa3b, v3
	v_exp_f32_e32 v24, v7
	v_mul_f32_e32 v7, 0xbfb8aa3b, v0
	v_exp_f32_e32 v25, v7
	s_nop 0
	v_pk_add_f32 v[24:25], v[24:25], 1.0 op_sel_hi:[1,0]
	s_nop 0
	v_div_scale_f32 v7, s[2:3], v25, v25, v0
	v_rcp_f32_e32 v15, v7
	s_nop 0
	v_fma_f32 v19, -v7, v15, 1.0
	v_fmac_f32_e32 v15, v19, v15
	v_div_scale_f32 v19, vcc, v0, v25, v0
	v_mul_f32_e32 v26, v19, v15
	v_fma_f32 v27, -v7, v26, v19
	v_fmac_f32_e32 v26, v27, v15
	v_fma_f32 v7, -v7, v26, v19
	v_div_fmas_f32 v7, v7, v15, v26
	v_div_fixup_f32 v25, v7, v25, v0
	v_div_scale_f32 v0, s[2:3], v24, v24, v3
	v_rcp_f32_e32 v7, v0
	s_nop 0
	v_fma_f32 v15, -v0, v7, 1.0
	v_fmac_f32_e32 v7, v15, v7
	v_div_scale_f32 v15, vcc, v3, v24, v3
	v_mul_f32_e32 v19, v15, v7
	v_fma_f32 v26, -v0, v19, v15
	v_fmac_f32_e32 v19, v26, v7
	v_fma_f32 v0, -v0, v19, v15
	v_div_fmas_f32 v0, v0, v7, v19
	v_div_fixup_f32 v24, v0, v24, v3
	v_lshlrev_b32_e32 v3, 16, v1
	v_and_b32_e32 v7, 0xffff0000, v1
	v_mul_f32_e32 v0, 0xbfb8aa3b, v3
	v_mul_f32_e32 v1, 0xbfb8aa3b, v7
	v_exp_f32_e32 v0, v0
	v_exp_f32_e32 v1, v1
	v_pk_mul_f32 v[20:21], v[20:21], v[24:25]
	v_pk_add_f32 v[0:1], v[0:1], 1.0 op_sel_hi:[1,0]
	s_nop 0
	v_div_scale_f32 v15, s[2:3], v1, v1, v7
	v_rcp_f32_e32 v19, v15
	v_cvt_pk_bf16_f32 v20, v20, v21
	v_fma_f32 v21, -v15, v19, 1.0
	v_fmac_f32_e32 v19, v21, v19
	v_div_scale_f32 v21, vcc, v7, v1, v7
	v_mul_f32_e32 v24, v21, v19
	v_fma_f32 v25, -v15, v24, v21
	v_fmac_f32_e32 v24, v25, v19
	v_fma_f32 v15, -v15, v24, v21
	v_div_fmas_f32 v15, v15, v19, v24
	v_div_fixup_f32 v1, v15, v1, v7
	v_div_scale_f32 v7, s[2:3], v0, v0, v3
	v_rcp_f32_e32 v15, v7
	s_nop 0
	v_fma_f32 v19, -v7, v15, 1.0
	v_fmac_f32_e32 v15, v19, v15
	v_div_scale_f32 v19, vcc, v3, v0, v3
	v_mul_f32_e32 v21, v19, v15
	v_fma_f32 v24, -v7, v21, v19
	v_fmac_f32_e32 v21, v24, v15
	v_fma_f32 v7, -v7, v21, v19
	v_div_fmas_f32 v7, v7, v15, v21
	v_div_fixup_f32 v0, v7, v0, v3
	v_pk_mul_f32 v[0:1], v[22:23], v[0:1]
	s_nop 0
	v_cvt_pk_bf16_f32 v21, v0, v1
	v_lshl_add_u64 v[0:1], v[16:17], 0, v[12:13]
	v_mov_b64_e32 v[12:13], v[168:169]
	s_nop 0
	v_lshlrev_b32_e32 v3, 16, v12
	v_and_b32_e32 v7, 0xffff0000, v12
	v_mul_f32_e32 v12, 0xbfb8aa3b, v3
	v_exp_f32_e32 v16, v12
	v_mul_f32_e32 v12, 0xbfb8aa3b, v7
	v_exp_f32_e32 v17, v12
	global_store_dwordx2 v[0:1], v[20:21], off
	ds_read_b128 v[20:23], v5 offset:22848
	v_pk_add_f32 v[16:17], v[16:17], 1.0 op_sel_hi:[1,0]
	s_nop 0
	v_div_scale_f32 v12, s[2:3], v17, v17, v7
	v_rcp_f32_e32 v15, v12
	s_waitcnt lgkmcnt(0)
	v_pk_mul_f32 v[20:21], v[4:5], v[20:21] op_sel_hi:[0,1]
	v_fma_f32 v19, -v12, v15, 1.0
	v_fmac_f32_e32 v15, v19, v15
	v_div_scale_f32 v19, vcc, v7, v17, v7
	v_mul_f32_e32 v24, v19, v15
	v_fma_f32 v25, -v12, v24, v19
	v_fmac_f32_e32 v24, v25, v15
	v_fma_f32 v12, -v12, v24, v19
	v_div_fmas_f32 v12, v12, v15, v24
	v_div_fixup_f32 v17, v12, v17, v7
	v_div_scale_f32 v7, s[2:3], v16, v16, v3
	v_rcp_f32_e32 v12, v7
	s_nop 0
	v_fma_f32 v15, -v7, v12, 1.0
	v_fmac_f32_e32 v12, v15, v12
	v_div_scale_f32 v15, vcc, v3, v16, v3
	v_mul_f32_e32 v19, v15, v12
	v_fma_f32 v24, -v7, v19, v15
	v_fmac_f32_e32 v19, v24, v12
	v_fma_f32 v7, -v7, v19, v15
	v_div_fmas_f32 v7, v7, v12, v19
	v_div_fixup_f32 v16, v7, v16, v3
	v_lshlrev_b32_e32 v3, 16, v13
	v_pk_mul_f32 v[16:17], v[20:21], v[16:17]
	v_and_b32_e32 v7, 0xffff0000, v13
	v_mul_f32_e32 v13, 0xbfb8aa3b, v3
	v_cvt_pk_bf16_f32 v12, v16, v17
	v_exp_f32_e32 v16, v13
	v_mul_f32_e32 v13, 0xbfb8aa3b, v7
	v_exp_f32_e32 v17, v13
	v_pk_mul_f32 v[20:21], v[4:5], v[22:23] op_sel_hi:[0,1]
	v_pk_add_f32 v[16:17], v[16:17], 1.0 op_sel_hi:[1,0]
	s_nop 0
	v_div_scale_f32 v13, s[2:3], v17, v17, v7
	v_rcp_f32_e32 v15, v13
	s_nop 0
	v_fma_f32 v19, -v13, v15, 1.0
	v_fmac_f32_e32 v15, v19, v15
	v_div_scale_f32 v19, vcc, v7, v17, v7
	v_mul_f32_e32 v22, v19, v15
	v_fma_f32 v23, -v13, v22, v19
	v_fmac_f32_e32 v22, v23, v15
	v_fma_f32 v13, -v13, v22, v19
	v_div_fmas_f32 v13, v13, v15, v22
	v_div_fixup_f32 v17, v13, v17, v7
	v_div_scale_f32 v7, s[2:3], v16, v16, v3
	v_rcp_f32_e32 v13, v7
	s_nop 0
	v_fma_f32 v15, -v7, v13, 1.0
	v_fmac_f32_e32 v13, v15, v13
	v_div_scale_f32 v15, vcc, v3, v16, v3
	v_mul_f32_e32 v19, v15, v13
	v_fma_f32 v22, -v7, v19, v15
	v_fmac_f32_e32 v19, v22, v13
	v_fma_f32 v7, -v7, v19, v15
	v_div_fmas_f32 v7, v7, v13, v19
	v_div_fixup_f32 v16, v7, v16, v3
	v_pk_mul_f32 v[16:17], v[20:21], v[16:17]
	ds_read_b128 v[20:23], v5 offset:22912
	v_cvt_pk_bf16_f32 v13, v16, v17
	global_store_dwordx2 v[0:1], v[12:13], off offset:32
	v_mov_b64_e32 v[12:13], v[170:171]
	s_waitcnt lgkmcnt(0)
	v_pk_mul_f32 v[20:21], v[4:5], v[20:21] op_sel_hi:[0,1]
	v_mov_b64_e32 v[8:9], v[172:173]
	s_nop 0
	v_lshlrev_b32_e32 v3, 16, v12
	v_and_b32_e32 v7, 0xffff0000, v12
	v_mul_f32_e32 v12, 0xbfb8aa3b, v3
	v_exp_f32_e32 v16, v12
	v_mul_f32_e32 v12, 0xbfb8aa3b, v7
	v_exp_f32_e32 v17, v12
	s_nop 0
	v_pk_add_f32 v[16:17], v[16:17], 1.0 op_sel_hi:[1,0]
	s_nop 0
	v_div_scale_f32 v12, s[2:3], v17, v17, v7
	v_rcp_f32_e32 v15, v12
	s_nop 0
	v_fma_f32 v19, -v12, v15, 1.0
	v_fmac_f32_e32 v15, v19, v15
	v_div_scale_f32 v19, vcc, v7, v17, v7
	v_mul_f32_e32 v24, v19, v15
	v_fma_f32 v25, -v12, v24, v19
	v_fmac_f32_e32 v24, v25, v15
	v_fma_f32 v12, -v12, v24, v19
	v_div_fmas_f32 v12, v12, v15, v24
	v_div_fixup_f32 v17, v12, v17, v7
	v_div_scale_f32 v7, s[2:3], v16, v16, v3
	v_rcp_f32_e32 v12, v7
	s_nop 0
	v_fma_f32 v15, -v7, v12, 1.0
	v_fmac_f32_e32 v12, v15, v12
	v_div_scale_f32 v15, vcc, v3, v16, v3
	v_mul_f32_e32 v19, v15, v12
	v_fma_f32 v24, -v7, v19, v15
	v_fmac_f32_e32 v19, v24, v12
	v_fma_f32 v7, -v7, v19, v15
	v_div_fmas_f32 v7, v7, v12, v19
	v_div_fixup_f32 v16, v7, v16, v3
	v_lshlrev_b32_e32 v3, 16, v13
	v_pk_mul_f32 v[16:17], v[20:21], v[16:17]
	v_and_b32_e32 v7, 0xffff0000, v13
	v_mul_f32_e32 v13, 0xbfb8aa3b, v3
	v_cvt_pk_bf16_f32 v12, v16, v17
	v_exp_f32_e32 v16, v13
	v_mul_f32_e32 v13, 0xbfb8aa3b, v7
	v_exp_f32_e32 v17, v13
	v_pk_mul_f32 v[20:21], v[4:5], v[22:23] op_sel_hi:[0,1]
	v_pk_add_f32 v[16:17], v[16:17], 1.0 op_sel_hi:[1,0]
	s_nop 0
	v_div_scale_f32 v13, s[2:3], v17, v17, v7
	v_rcp_f32_e32 v15, v13
	s_nop 0
	v_fma_f32 v19, -v13, v15, 1.0
	v_fmac_f32_e32 v15, v19, v15
	v_div_scale_f32 v19, vcc, v7, v17, v7
	v_mul_f32_e32 v22, v19, v15
	v_fma_f32 v23, -v13, v22, v19
	v_fmac_f32_e32 v22, v23, v15
	v_fma_f32 v13, -v13, v22, v19
	v_div_fmas_f32 v13, v13, v15, v22
	v_div_fixup_f32 v17, v13, v17, v7
	v_div_scale_f32 v7, s[2:3], v16, v16, v3
	v_rcp_f32_e32 v13, v7
	s_nop 0
	v_fma_f32 v15, -v7, v13, 1.0
	v_fmac_f32_e32 v13, v15, v13
	v_div_scale_f32 v15, vcc, v3, v16, v3
	v_mul_f32_e32 v19, v15, v13
	v_fma_f32 v22, -v7, v19, v15
	v_fmac_f32_e32 v19, v22, v13
	v_fma_f32 v7, -v7, v19, v15
	v_div_fmas_f32 v7, v7, v13, v19
	v_div_fixup_f32 v16, v7, v16, v3
	v_pk_mul_f32 v[16:17], v[20:21], v[16:17]
	s_nop 0
	v_lshlrev_b32_e32 v3, 16, v8
	v_cvt_pk_bf16_f32 v13, v16, v17
	ds_read_b128 v[20:23], v5 offset:22976
	v_and_b32_e32 v5, 0xffff0000, v8
	v_mul_f32_e32 v7, 0xbfb8aa3b, v3
	global_store_dwordx2 v[0:1], v[12:13], off offset:64
	v_exp_f32_e32 v12, v7
	v_mul_f32_e32 v7, 0xbfb8aa3b, v5
	v_exp_f32_e32 v13, v7
	s_waitcnt lgkmcnt(0)
	v_pk_mul_f32 v[16:17], v[4:5], v[20:21] op_sel_hi:[0,1]
	v_pk_add_f32 v[12:13], v[12:13], 1.0 op_sel_hi:[1,0]
	s_nop 0
	v_div_scale_f32 v7, s[2:3], v13, v13, v5
	v_rcp_f32_e32 v8, v7
	s_nop 0
	v_fma_f32 v15, -v7, v8, 1.0
	v_fmac_f32_e32 v8, v15, v8
	v_div_scale_f32 v15, vcc, v5, v13, v5
	v_mul_f32_e32 v19, v15, v8
	v_fma_f32 v20, -v7, v19, v15
	v_fmac_f32_e32 v19, v20, v8
	v_fma_f32 v7, -v7, v19, v15
	v_div_fmas_f32 v7, v7, v8, v19
	v_div_fixup_f32 v13, v7, v13, v5
	v_div_scale_f32 v5, s[2:3], v12, v12, v3
	v_rcp_f32_e32 v7, v5
	s_nop 0
	v_fma_f32 v8, -v5, v7, 1.0
	v_fmac_f32_e32 v7, v8, v7
	v_div_scale_f32 v8, vcc, v3, v12, v3
	v_mul_f32_e32 v15, v8, v7
	v_fma_f32 v19, -v5, v15, v8
	v_fmac_f32_e32 v15, v19, v7
	v_fma_f32 v5, -v5, v15, v8
	v_div_fmas_f32 v5, v5, v7, v15
	v_div_fixup_f32 v12, v5, v12, v3
	v_lshlrev_b32_e32 v3, 16, v9
	v_and_b32_e32 v7, 0xffff0000, v9
	v_pk_mul_f32 v[12:13], v[16:17], v[12:13]
	v_mul_f32_e32 v5, 0xbfb8aa3b, v3
	v_mul_f32_e32 v9, 0xbfb8aa3b, v7
	v_cvt_pk_bf16_f32 v8, v12, v13
	v_exp_f32_e32 v12, v5
	v_exp_f32_e32 v13, v9
	v_pk_mul_f32 v[4:5], v[4:5], v[22:23] op_sel_hi:[0,1]
	v_pk_add_f32 v[12:13], v[12:13], 1.0 op_sel_hi:[1,0]
	s_nop 0
	v_div_scale_f32 v9, s[2:3], v13, v13, v7
	v_rcp_f32_e32 v15, v9
	s_nop 0
	v_fma_f32 v16, -v9, v15, 1.0
	v_fmac_f32_e32 v15, v16, v15
	v_div_scale_f32 v16, vcc, v7, v13, v7
	v_mul_f32_e32 v17, v16, v15
	v_fma_f32 v19, -v9, v17, v16
	v_fmac_f32_e32 v17, v19, v15
	v_fma_f32 v9, -v9, v17, v16
	v_div_fmas_f32 v9, v9, v15, v17
	v_div_fixup_f32 v13, v9, v13, v7
	v_div_scale_f32 v7, s[2:3], v12, v12, v3
	v_rcp_f32_e32 v9, v7
	s_xor_b64 s[2:3], exec, -1
	v_fma_f32 v15, -v7, v9, 1.0
	v_fmac_f32_e32 v9, v15, v9
	v_div_scale_f32 v15, vcc, v3, v12, v3
	v_mul_f32_e32 v16, v15, v9
	v_fma_f32 v17, -v7, v16, v15
	v_fmac_f32_e32 v16, v17, v9
	v_fma_f32 v7, -v7, v16, v15
	v_div_fmas_f32 v7, v7, v9, v16
	v_div_fixup_f32 v12, v7, v12, v3
	v_pk_mul_f32 v[4:5], v[4:5], v[12:13]
	s_nop 0
	v_cvt_pk_bf16_f32 v9, v4, v5
	global_store_dwordx2 v[0:1], v[8:9], off offset:96

.LBB0_585:
	s_ashr_i32 s3, s44, 7
	s_and_b32 s8, s44, 0x7f
	v_mov_b32_e32 v15, v197
	s_lshl_b32 s2, s3, 12
	s_lshl_b32 s9, s8, 5
	s_or_b32 s2, s2, s9
	v_and_b32_e32 v130, 15, v197
	v_or_b32_e32 v130, s2, v130
	v_mov_b64_e32 v[132:133], s[4:5]
	v_mad_i64_i32 v[132:133], s[100:101], v130, s93, v[132:133]
	v_lshrrev_b32_e32 v131, 6, v197
	v_lshlrev_b32_e32 v131, 7, v131
	v_bfe_u32 v134, v197, 4, 2
	v_lshl_add_u32 v131, v134, 3, v131
	v_add_u32_e32 v134, 0x1800, v131
	v_mov_b32_e32 v135, 0
	v_lshl_add_u64 v[132:133], v[132:133], 0, v[134:135]
	global_load_dwordx2 v[136:137], v[132:133], off
	global_load_dwordx2 v[138:139], v[132:133], off offset:32
	global_load_dwordx2 v[140:141], v[132:133], off offset:64
	global_load_dwordx2 v[142:143], v[132:133], off offset:96
	s_mov_b64 s[100:101], 0x1a800
	v_lshl_add_u64 v[132:133], v[132:133], 0, s[100:101]
	v_and_b32_e32 v152, 48, v197
	global_load_dwordx4 v[156:159], v152, s[42:43]
	global_load_dwordx4 v[160:163], v152, s[42:43] offset:64
	global_load_dwordx4 v[164:167], v152, s[42:43] offset:128
	global_load_dwordx4 v[168:171], v152, s[42:43] offset:192
	global_load_dwordx2 v[144:145], v[132:133], off
	global_load_dwordx2 v[146:147], v[132:133], off offset:32
	global_load_dwordx2 v[148:149], v[132:133], off offset:64
	global_load_dwordx2 v[150:151], v[132:133], off offset:96
	v_ashrrev_i32_e32 v1, 6, v15
	v_bfe_u32 v4, v15, 5, 1
	v_or_b32_e32 v8, s2, v4
	v_mov_b64_e32 v[4:5], s[4:5]
	v_lshlrev_b32_e32 v16, 5, v1
	v_lshlrev_b32_e32 v0, 11, v1
	s_movk_i32 s9, 0xa00
	v_mad_i64_i32 v[8:9], s[10:11], v8, s93, v[4:5]
	v_ashrrev_i32_e32 v17, 31, v16
	v_and_b32_e32 v19, 31, v15
	v_mad_u64_u32 v[12:13], s[10:11], v1, s9, v[0:1]
	v_lshl_add_u64 v[8:9], v[16:17], 1, v[8:9]
	v_lshlrev_b32_e32 v16, 1, v19
	v_mov_b32_e32 v17, v2
	v_lshl_add_u64 v[8:9], v[8:9], 0, v[16:17]
	s_mov_b64 s[10:11], 0x3500
	v_lshl_add_u64 v[16:17], v[8:9], 0, s[10:11]
	v_add_co_u32_e32 v8, vcc, s94, v8
	v_bfe_u32 v89, v15, 3, 3
	s_nop 0
	v_addc_co_u32_e32 v9, vcc, 0, v9, vcc
	global_load_ushort v87, v[8:9], off offset:1024
	global_load_ushort v86, v[8:9], off offset:1280
	v_lshlrev_b32_e32 v88, 4, v15
	v_lshl_add_u64 v[8:9], v[16:17], 0, s[10:11]
	v_add_co_u32_e32 v16, vcc, s94, v16
	v_and_b32_e32 v3, 63, v15
	s_nop 0
	v_addc_co_u32_e32 v17, vcc, 0, v17, vcc
	flat_load_ushort v85, v[16:17] offset:1024
	flat_load_ushort v84, v[16:17] offset:1280
	v_or_b32_e32 v74, 64, v3
	v_lshl_add_u64 v[16:17], v[8:9], 0, s[10:11]
	v_add_co_u32_e32 v8, vcc, s94, v8
	v_lshrrev_b32_e32 v122, 3, v74
	s_nop 0
	v_addc_co_u32_e32 v9, vcc, 0, v9, vcc
	flat_load_ushort v83, v[8:9] offset:1024
	flat_load_ushort v82, v[8:9] offset:1280
	v_or_b32_e32 v75, 0x80, v3
	v_lshl_add_u64 v[8:9], v[16:17], 0, s[10:11]
	v_add_co_u32_e32 v16, vcc, s94, v16
	v_lshrrev_b32_e32 v123, 3, v75
	s_nop 0
	v_addc_co_u32_e32 v17, vcc, 0, v17, vcc
	flat_load_ushort v81, v[16:17] offset:1024
	flat_load_ushort v80, v[16:17] offset:1280
	v_or_b32_e32 v76, 0xc0, v3
	v_lshl_add_u64 v[16:17], v[8:9], 0, s[10:11]
	v_add_co_u32_e32 v8, vcc, s94, v8
	v_lshrrev_b32_e32 v124, 3, v76
	s_nop 0
	v_addc_co_u32_e32 v9, vcc, 0, v9, vcc
	flat_load_ushort v79, v[8:9] offset:1024
	flat_load_ushort v78, v[8:9] offset:1280
	s_ashr_i32 s45, s44, 31
	v_lshl_add_u64 v[8:9], v[16:17], 0, s[10:11]
	v_add_co_u32_e32 v16, vcc, s94, v16
	v_lshlrev_b32_e32 v22, 4, v3
	s_nop 0
	v_addc_co_u32_e32 v17, vcc, 0, v17, vcc
	flat_load_ushort v77, v[16:17] offset:1024
	flat_load_ushort v73, v[16:17] offset:1280
	v_mov_b32_e32 v23, v2
	v_lshl_add_u64 v[16:17], v[8:9], 0, s[10:11]
	v_add_co_u32_e32 v8, vcc, s94, v8
	v_lshlrev_b32_e32 v118, 2, v15
	s_nop 0
	v_addc_co_u32_e32 v9, vcc, 0, v9, vcc
	flat_load_ushort v72, v[8:9] offset:1024
	flat_load_ushort v71, v[8:9] offset:1280
	v_ashrrev_i32_e32 v119, 31, v118
	v_lshl_add_u64 v[8:9], v[16:17], 0, s[10:11]
	v_add_co_u32_e32 v16, vcc, s94, v16
	v_add_u32_e32 v110, 0x400, v118
	s_nop 0
	v_addc_co_u32_e32 v17, vcc, 0, v17, vcc
	flat_load_ushort v70, v[16:17] offset:1024
	flat_load_ushort v69, v[16:17] offset:1280
	v_ashrrev_i32_e32 v111, 31, v110
	v_lshl_add_u64 v[16:17], v[8:9], 0, s[10:11]
	v_add_co_u32_e32 v8, vcc, s94, v8
	v_add_u32_e32 v114, 0x800, v118
	s_nop 0
	v_addc_co_u32_e32 v9, vcc, 0, v9, vcc
	flat_load_ushort v68, v[8:9] offset:1024
	flat_load_ushort v67, v[8:9] offset:1280
	v_ashrrev_i32_e32 v115, 31, v114
	v_lshl_add_u64 v[8:9], v[16:17], 0, s[10:11]
	v_add_co_u32_e32 v16, vcc, s94, v16
	v_lshlrev_b32_e32 v13, 3, v15
	s_nop 0
	v_addc_co_u32_e32 v17, vcc, 0, v17, vcc
	flat_load_ushort v66, v[16:17] offset:1024
	flat_load_ushort v65, v[16:17] offset:1280
	s_waitcnt vmcnt(0)
	v_lshlrev_b32_e32 v86, 16, v86
	v_lshl_add_u64 v[16:17], v[8:9], 0, s[10:11]
	v_add_co_u32_e32 v8, vcc, s94, v8
	v_lshlrev_b32_e32 v87, 16, v87
	s_nop 0
	v_addc_co_u32_e32 v9, vcc, 0, v9, vcc
	flat_load_ushort v64, v[8:9] offset:1024
	flat_load_ushort v63, v[8:9] offset:1280
	s_waitcnt lgkmcnt(0)
	v_lshlrev_b32_e32 v85, 16, v85
	v_lshl_add_u64 v[8:9], v[16:17], 0, s[10:11]
	v_add_co_u32_e32 v16, vcc, s94, v16
	v_lshlrev_b32_e32 v84, 16, v84
	s_nop 0
	v_addc_co_u32_e32 v17, vcc, 0, v17, vcc
	flat_load_ushort v62, v[16:17] offset:1024
	flat_load_ushort v61, v[16:17] offset:1280
	v_lshlrev_b32_e32 v83, 16, v83
	v_lshl_add_u64 v[16:17], v[8:9], 0, s[10:11]
	v_add_co_u32_e32 v8, vcc, s94, v8
	v_lshlrev_b32_e32 v82, 16, v82
	s_nop 0
	v_addc_co_u32_e32 v9, vcc, 0, v9, vcc
	flat_load_ushort v60, v[8:9] offset:1024
	flat_load_ushort v59, v[8:9] offset:1280
	v_lshlrev_b32_e32 v81, 16, v81
	v_lshl_add_u64 v[8:9], v[16:17], 0, s[10:11]
	v_add_co_u32_e32 v16, vcc, s94, v16
	v_lshlrev_b32_e32 v80, 16, v80
	s_nop 0
	v_addc_co_u32_e32 v17, vcc, 0, v17, vcc
	flat_load_ushort v58, v[16:17] offset:1024
	flat_load_ushort v57, v[16:17] offset:1280
	v_lshlrev_b32_e32 v79, 16, v79
	v_lshl_add_u64 v[16:17], v[8:9], 0, s[10:11]
	v_add_co_u32_e32 v8, vcc, s94, v8
	v_lshlrev_b32_e32 v78, 16, v78
	s_nop 0
	v_addc_co_u32_e32 v9, vcc, 0, v9, vcc
	flat_load_ushort v56, v[8:9] offset:1024
	flat_load_ushort v55, v[8:9] offset:1280
	v_lshlrev_b32_e32 v77, 16, v77
	v_lshl_add_u64 v[8:9], v[16:17], 0, s[10:11]
	v_add_co_u32_e32 v16, vcc, s94, v16
	v_lshlrev_b32_e32 v73, 16, v73
	s_nop 0
	v_addc_co_u32_e32 v17, vcc, 0, v17, vcc
	flat_load_ushort v54, v[16:17] offset:1024
	flat_load_ushort v53, v[16:17] offset:1280
	v_or_b32_e32 v16, s2, v89
	v_and_b32_e32 v8, 0xffffffc0, v15
	v_ashrrev_i32_e32 v9, 31, v8
	v_mad_i64_i32 v[16:17], s[10:11], v16, s93, v[4:5]
	v_lshlrev_b64 v[8:9], 1, v[8:9]
	v_lshl_add_u64 v[20:21], v[16:17], 0, v[8:9]
	v_and_b32_e32 v16, 0x70, v88
	v_mov_b32_e32 v17, v2
	v_lshl_add_u64 v[20:21], v[20:21], 0, v[16:17]
	v_add_co_u32_e32 v20, vcc, s94, v20
	v_lshlrev_b32_e32 v72, 16, v72
	s_nop 0
	v_addc_co_u32_e32 v21, vcc, 0, v21, vcc
	global_load_dwordx4 v[90:93], v[20:21], off offset:1536
	v_or_b32_e32 v20, s2, v122
	v_mad_i64_i32 v[20:21], s[10:11], v20, s93, v[4:5]
	v_lshl_add_u64 v[20:21], v[20:21], 0, v[8:9]
	v_lshl_add_u64 v[20:21], v[20:21], 0, v[16:17]
	v_add_co_u32_e32 v20, vcc, s94, v20
	v_lshlrev_b32_e32 v71, 16, v71
	s_nop 0
	v_addc_co_u32_e32 v21, vcc, 0, v21, vcc
	global_load_dwordx4 v[94:97], v[20:21], off offset:1536
	v_or_b32_e32 v20, s2, v123
	v_mad_i64_i32 v[20:21], s[10:11], v20, s93, v[4:5]
	v_lshl_add_u64 v[20:21], v[20:21], 0, v[8:9]
	v_lshl_add_u64 v[20:21], v[20:21], 0, v[16:17]
	v_add_co_u32_e32 v20, vcc, s94, v20
	v_lshlrev_b32_e32 v70, 16, v70
	s_nop 0
	v_addc_co_u32_e32 v21, vcc, 0, v21, vcc
	global_load_dwordx4 v[98:101], v[20:21], off offset:1536
	v_or_b32_e32 v20, s2, v124
	v_mad_i64_i32 v[20:21], s[10:11], v20, s93, v[4:5]
	v_lshl_add_u64 v[20:21], v[20:21], 0, v[8:9]
	v_lshl_add_u64 v[20:21], v[20:21], 0, v[16:17]
	v_add_co_u32_e32 v20, vcc, s94, v20
	v_lshlrev_b32_e32 v17, 7, v1
	s_nop 0
	v_addc_co_u32_e32 v21, vcc, 0, v21, vcc
	global_load_dwordx4 v[102:105], v[20:21], off offset:1536
	v_lshl_add_u32 v20, s3, 9, v17
	v_or_b32_e32 v20, s8, v20
	v_ashrrev_i32_e32 v21, 31, v20
	v_readlane_b32 s8, v249, 50
	v_lshlrev_b64 v[20:21], 13, v[20:21]
	v_readlane_b32 s9, v249, 51
	v_readlane_b32 s10, v249, 48
	v_readlane_b32 s11, v249, 49
	v_lshl_add_u64 v[20:21], s[8:9], 0, v[20:21]
	s_lshl_b64 s[8:9], s[44:45], 14
	v_lshl_add_u64 v[20:21], v[20:21], 0, v[22:23]
	s_add_u32 s8, s10, s8
	global_load_dwordx4 v[48:51], v[20:21], off nt
	global_load_dwordx4 v[44:47], v[20:21], off offset:1024 nt
	global_load_dwordx4 v[40:43], v[20:21], off offset:2048 nt
	global_load_dwordx4 v[36:39], v[20:21], off offset:3072 nt
	v_add_co_u32_e32 v20, vcc, s94, v20
	s_addc_u32 s9, s11, s9
	s_nop 0
	v_addc_co_u32_e32 v21, vcc, 0, v21, vcc
	v_lshl_add_u64 v[106:107], v[118:119], 2, s[8:9]
	global_load_dwordx4 v[32:35], v[20:21], off nt
	global_load_dwordx4 v[28:31], v[20:21], off offset:1024 nt
	global_load_dwordx4 v[24:27], v[20:21], off offset:2048 nt
	s_nop 0
	global_load_dwordx4 v[20:23], v[20:21], off offset:3072 nt
	v_lshl_add_u64 v[110:111], v[110:111], 2, s[8:9]
	global_load_dwordx4 v[106:109], v[106:107], off nt
	v_add_u32_e32 v118, 0xc00, v118
	global_load_dwordx4 v[110:113], v[110:111], off nt
	v_lshl_add_u64 v[114:115], v[114:115], 2, s[8:9]
	v_ashrrev_i32_e32 v119, 31, v118
	global_load_dwordx4 v[114:117], v[114:115], off nt
	v_lshl_add_u64 v[118:119], v[118:119], 2, s[8:9]
	global_load_dwordx4 v[118:121], v[118:119], off nt
	v_or_b32_e32 v16, v12, v16
	v_mad_u32_u24 v89, v89, s0, v16
	s_waitcnt lgkmcnt(0)
	s_barrier
	s_movk_i32 s3, 0x60
	v_lshlrev_b32_e32 v69, 16, v69
	v_lshlrev_b32_e32 v68, 16, v68
	v_lshlrev_b32_e32 v67, 16, v67
	v_lshlrev_b32_e32 v66, 16, v66
	v_lshlrev_b32_e32 v65, 16, v65
	s_waitcnt vmcnt(0)
	v_lshlrev_b32_e32 v64, 16, v64
	v_lshlrev_b32_e32 v63, 16, v63
	v_lshlrev_b32_e32 v62, 16, v62
	v_lshlrev_b32_e32 v61, 16, v61
	v_lshlrev_b32_e32 v60, 16, v60
	v_lshlrev_b32_e32 v59, 16, v59
	ds_write_b128 v89, v[90:93] offset:34816
	v_mad_u32_u24 v89, v122, s0, v16
	v_lshlrev_b32_e32 v58, 16, v58
	v_lshlrev_b32_e32 v57, 16, v57
	v_lshlrev_b32_e32 v56, 16, v56
	v_lshlrev_b32_e32 v55, 16, v55
	v_bfe_u32 v52, v15, 4, 2
	v_and_b32_e32 v7, 15, v15
	s_mov_b64 s[8:9], 0x1800
	s_mov_b64 s[10:11], 0x15a0600
	s_add_i32 s44, s44, s26
	ds_write_b128 v89, v[94:97] offset:34816
	v_mad_u32_u24 v89, v123, s0, v16
	v_mad_u32_u24 v16, v124, s0, v16
	s_cmpk_lt_i32 s44, 0x200
	s_mov_b32 s40, s74
	ds_write_b128 v89, v[98:101] offset:34816
	ds_write_b128 v16, v[102:105] offset:34816
	ds_write_b128 v88, v[106:109]
	ds_write_b128 v88, v[110:113] offset:4096
	ds_write_b128 v88, v[114:117] offset:8192
	ds_write_b128 v88, v[118:121] offset:12288
	v_lshl_or_b32 v16, v19, 2, v17
	v_and_b32_e32 v17, 0x200, v88
	v_add_u32_e32 v17, v16, v17
	s_waitcnt lgkmcnt(0)
	s_barrier
	ds_read_b32 v17, v17
	v_cvt_pk_bf16_f32 v48, v48, v49
	v_cvt_pk_bf16_f32 v49, v50, v51
	v_cvt_pk_bf16_f32 v44, v44, v45
	v_cvt_pk_bf16_f32 v45, v46, v47
	s_waitcnt lgkmcnt(0)
	v_mul_f32_e32 v88, 0x3fb8aa3b, v17
	v_mul_f32_e32 v17, 0xbfb8aa3b, v17
	v_exp_f32_e32 v17, v17
	v_exp_f32_e32 v88, v88
	v_cvt_pk_bf16_f32 v40, v40, v41
	v_cvt_pk_bf16_f32 v41, v42, v43
	v_mul_f32_e32 v17, v17, v86
	v_mul_f32_e32 v87, v88, v87
	v_lshl_or_b32 v88, v3, 1, v0
	v_cvt_pk_bf16_f32 v17, v17, s0
	ds_write_b16 v88, v17 offset:26624
	v_lshlrev_b32_e32 v17, 4, v74
	v_and_b32_e32 v17, 0x600, v17
	v_add_u32_e32 v17, v16, v17
	ds_read_b32 v17, v17
	v_mul_f32_e32 v87, 0x3e3504f3, v87
	v_cvt_pk_bf16_f32 v87, v87, s0
	ds_write_b16 v88, v87 offset:18432
	v_cvt_pk_bf16_f32 v36, v36, v37
	s_waitcnt lgkmcnt(1)
	v_mul_f32_e32 v86, 0x3fb8aa3b, v17
	v_mul_f32_e32 v17, 0xbfb8aa3b, v17
	v_exp_f32_e32 v86, v86
	v_exp_f32_e32 v17, v17
	v_cvt_pk_bf16_f32 v37, v38, v39
	v_cvt_pk_bf16_f32 v32, v32, v33
	v_mul_f32_e32 v85, v86, v85
	v_and_or_b32 v86, v74, s3, v19
	v_mul_f32_e32 v17, v17, v84
	v_lshl_or_b32 v86, v86, 1, v0
	v_cvt_pk_bf16_f32 v17, v17, s0
	ds_write_b16 v86, v17 offset:26624
	v_lshlrev_b32_e32 v17, 4, v75
	v_and_b32_e32 v17, 0xa00, v17
	v_add_u32_e32 v17, v16, v17
	ds_read_b32 v17, v17
	s_movk_i32 s3, 0xa0
	v_mul_f32_e32 v85, 0x3e3504f3, v85
	v_cvt_pk_bf16_f32 v85, v85, s0
	ds_write_b16 v86, v85 offset:18432
	s_waitcnt lgkmcnt(1)
	v_mul_f32_e32 v84, 0x3fb8aa3b, v17
	v_mul_f32_e32 v17, 0xbfb8aa3b, v17
	v_exp_f32_e32 v84, v84
	v_exp_f32_e32 v17, v17
	v_cvt_pk_bf16_f32 v33, v34, v35
	v_cvt_pk_bf16_f32 v28, v28, v29
	v_mul_f32_e32 v83, v84, v83
	v_and_or_b32 v84, v75, s3, v19
	v_mul_f32_e32 v17, v17, v82
	v_lshl_or_b32 v84, v84, 1, v0
	v_cvt_pk_bf16_f32 v17, v17, s0
	ds_write_b16 v84, v17 offset:26624
	v_lshlrev_b32_e32 v17, 4, v76
	v_and_b32_e32 v17, 0xe00, v17
	v_add_u32_e32 v17, v16, v17
	ds_read_b32 v17, v17
	s_movk_i32 s3, 0xe0
	v_mul_f32_e32 v83, 0x3e3504f3, v83
	v_cvt_pk_bf16_f32 v83, v83, s0
	ds_write_b16 v84, v83 offset:18432
	s_waitcnt lgkmcnt(1)
	v_mul_f32_e32 v82, 0x3fb8aa3b, v17
	v_mul_f32_e32 v17, 0xbfb8aa3b, v17
	v_exp_f32_e32 v82, v82
	v_exp_f32_e32 v17, v17
	v_cvt_pk_bf16_f32 v29, v30, v31
	v_cvt_pk_bf16_f32 v24, v24, v25
	v_mul_f32_e32 v81, v82, v81
	v_and_or_b32 v82, v76, s3, v19
	v_mul_f32_e32 v17, v17, v80
	v_lshl_or_b32 v82, v82, 1, v0
	v_cvt_pk_bf16_f32 v17, v17, s0
	v_or_b32_e32 v80, 0x100, v3
	ds_write_b16 v82, v17 offset:26624
	v_lshlrev_b32_e32 v17, 4, v80
	v_and_b32_e32 v17, 0x1200, v17
	v_add_u32_e32 v17, v16, v17
	ds_read_b32 v17, v17
	v_mul_f32_e32 v81, 0x3e3504f3, v81
	v_cvt_pk_bf16_f32 v81, v81, s0
	ds_write_b16 v82, v81 offset:18432
	s_movk_i32 s3, 0x120
	s_waitcnt lgkmcnt(1)
	v_mul_f32_e32 v81, 0x3fb8aa3b, v17
	v_mul_f32_e32 v17, 0xbfb8aa3b, v17
	v_exp_f32_e32 v81, v81
	v_exp_f32_e32 v17, v17
	v_cvt_pk_bf16_f32 v25, v26, v27
	v_cvt_pk_bf16_f32 v20, v20, v21
	v_mul_f32_e32 v79, v81, v79
	v_and_or_b32 v81, v80, s3, v19
	v_mul_f32_e32 v17, v17, v78
	v_lshl_or_b32 v81, v81, 1, v0
	v_cvt_pk_bf16_f32 v17, v17, s0
	v_or_b32_e32 v78, 0x140, v3
	ds_write_b16 v81, v17 offset:26624
	v_lshlrev_b32_e32 v17, 4, v78
	v_and_b32_e32 v17, 0x1600, v17
	v_add_u32_e32 v17, v16, v17
	ds_read_b32 v17, v17
	v_mul_f32_e32 v79, 0x3e3504f3, v79
	v_cvt_pk_bf16_f32 v79, v79, s0
	ds_write_b16 v81, v79 offset:18432
	s_movk_i32 s3, 0x160
	s_waitcnt lgkmcnt(1)
	v_mul_f32_e32 v79, 0x3fb8aa3b, v17
	v_mul_f32_e32 v17, 0xbfb8aa3b, v17
	v_exp_f32_e32 v79, v79
	v_exp_f32_e32 v17, v17
	v_cvt_pk_bf16_f32 v21, v22, v23
	v_mul_f32_e32 v77, v79, v77
	v_and_or_b32 v79, v78, s3, v19
	v_mul_f32_e32 v17, v17, v73
	v_lshl_or_b32 v79, v79, 1, v0
	v_cvt_pk_bf16_f32 v17, v17, s0
	v_or_b32_e32 v73, 0x180, v3
	ds_write_b16 v79, v17 offset:26624
	v_lshlrev_b32_e32 v17, 4, v73
	v_and_b32_e32 v17, 0x1a00, v17
	v_add_u32_e32 v17, v16, v17
	ds_read_b32 v17, v17
	v_mul_f32_e32 v77, 0x3e3504f3, v77
	v_cvt_pk_bf16_f32 v77, v77, s0
	ds_write_b16 v79, v77 offset:18432
	s_movk_i32 s3, 0x1a0
	s_waitcnt lgkmcnt(1)
	v_mul_f32_e32 v77, 0x3fb8aa3b, v17
	v_mul_f32_e32 v17, 0xbfb8aa3b, v17
	v_exp_f32_e32 v77, v77
	v_exp_f32_e32 v17, v17
	v_mul_f32_e32 v72, v77, v72
	v_and_or_b32 v77, v73, s3, v19
	v_mul_f32_e32 v17, v17, v71
	v_lshl_or_b32 v77, v77, 1, v0
	v_cvt_pk_bf16_f32 v17, v17, s0
	v_or_b32_e32 v71, 0x1c0, v3
	ds_write_b16 v77, v17 offset:26624
	v_lshlrev_b32_e32 v17, 4, v71
	v_and_b32_e32 v17, 0x1e00, v17
	v_add_u32_e32 v17, v16, v17
	ds_read_b32 v17, v17
	v_mul_f32_e32 v72, 0x3e3504f3, v72
	v_cvt_pk_bf16_f32 v72, v72, s0
	ds_write_b16 v77, v72 offset:18432
	s_movk_i32 s3, 0x1e0
	s_waitcnt lgkmcnt(1)
	v_mul_f32_e32 v72, 0x3fb8aa3b, v17
	v_mul_f32_e32 v17, 0xbfb8aa3b, v17
	v_exp_f32_e32 v72, v72
	v_exp_f32_e32 v17, v17
	v_mul_f32_e32 v70, v72, v70
	v_and_or_b32 v72, v71, s3, v19
	v_mul_f32_e32 v17, v17, v69
	v_lshl_or_b32 v72, v72, 1, v0
	v_cvt_pk_bf16_f32 v17, v17, s0
	ds_write_b16 v72, v17 offset:26624
	v_or_b32_e32 v17, 0x200, v3
	v_lshlrev_b32_e32 v69, 4, v17
	v_and_b32_e32 v69, 0x2200, v69
	v_add_u32_e32 v69, v16, v69
	ds_read_b32 v69, v69
	v_mul_f32_e32 v70, 0x3e3504f3, v70
	v_cvt_pk_bf16_f32 v70, v70, s0
	ds_write_b16 v72, v70 offset:18432
	s_movk_i32 s3, 0x220
	s_waitcnt lgkmcnt(1)
	v_mul_f32_e32 v70, 0x3fb8aa3b, v69
	v_exp_f32_e32 v70, v70
	v_and_or_b32 v17, v17, s3, v19
	v_lshl_or_b32 v17, v17, 1, v0
	s_movk_i32 s3, 0x260
	v_mul_f32_e32 v68, v70, v68
	v_mul_f32_e32 v68, 0x3e3504f3, v68
	v_cvt_pk_bf16_f32 v68, v68, s0
	ds_write_b16 v17, v68 offset:18432
	v_mul_f32_e32 v68, 0xbfb8aa3b, v69
	v_exp_f32_e32 v68, v68
	s_nop 0
	v_mul_f32_e32 v67, v68, v67
	v_cvt_pk_bf16_f32 v67, v67, s0
	ds_write_b16 v17, v67 offset:26624
	v_or_b32_e32 v17, 0x240, v3
	v_lshlrev_b32_e32 v67, 4, v17
	v_and_b32_e32 v67, 0x2600, v67
	v_add_u32_e32 v67, v16, v67
	ds_read_b32 v67, v67
	v_and_or_b32 v17, v17, s3, v19
	v_lshl_or_b32 v17, v17, 1, v0
	s_movk_i32 s3, 0x2a0
	s_waitcnt lgkmcnt(0)
	v_mul_f32_e32 v68, 0x3fb8aa3b, v67
	v_exp_f32_e32 v68, v68
	s_nop 0
	v_mul_f32_e32 v66, v68, v66
	v_mul_f32_e32 v66, 0x3e3504f3, v66
	v_cvt_pk_bf16_f32 v66, v66, s0
	ds_write_b16 v17, v66 offset:18432
	v_mul_f32_e32 v66, 0xbfb8aa3b, v67
	v_exp_f32_e32 v66, v66
	s_nop 0
	v_mul_f32_e32 v65, v66, v65
	v_cvt_pk_bf16_f32 v65, v65, s0
	ds_write_b16 v17, v65 offset:26624
	v_or_b32_e32 v17, 0x280, v3
	v_lshlrev_b32_e32 v65, 4, v17
	v_and_b32_e32 v65, 0x2a00, v65
	v_add_u32_e32 v65, v16, v65
	ds_read_b32 v65, v65
	v_and_or_b32 v17, v17, s3, v19
	v_lshl_or_b32 v17, v17, 1, v0
	s_movk_i32 s3, 0x2e0
	s_waitcnt lgkmcnt(0)
	v_mul_f32_e32 v66, 0x3fb8aa3b, v65
	v_exp_f32_e32 v66, v66
	s_nop 0
	v_mul_f32_e32 v64, v66, v64
	v_mul_f32_e32 v64, 0x3e3504f3, v64
	v_cvt_pk_bf16_f32 v64, v64, s0
	ds_write_b16 v17, v64 offset:18432
	v_mul_f32_e32 v64, 0xbfb8aa3b, v65
	v_exp_f32_e32 v64, v64
	s_nop 0
	v_mul_f32_e32 v63, v64, v63
	v_cvt_pk_bf16_f32 v63, v63, s0
	ds_write_b16 v17, v63 offset:26624
	v_or_b32_e32 v17, 0x2c0, v3
	v_lshlrev_b32_e32 v63, 4, v17
	v_and_b32_e32 v63, 0x2e00, v63
	v_add_u32_e32 v63, v16, v63
	ds_read_b32 v63, v63
	v_and_or_b32 v17, v17, s3, v19
	v_lshl_or_b32 v17, v17, 1, v0
	s_movk_i32 s3, 0x320
	s_waitcnt lgkmcnt(0)
	v_mul_f32_e32 v64, 0x3fb8aa3b, v63
	v_exp_f32_e32 v64, v64
	s_nop 0
	v_mul_f32_e32 v62, v64, v62
	v_mul_f32_e32 v62, 0x3e3504f3, v62
	v_cvt_pk_bf16_f32 v62, v62, s0
	ds_write_b16 v17, v62 offset:18432
	v_mul_f32_e32 v62, 0xbfb8aa3b, v63
	v_exp_f32_e32 v62, v62
	s_nop 0
	v_mul_f32_e32 v61, v62, v61
	v_cvt_pk_bf16_f32 v61, v61, s0
	ds_write_b16 v17, v61 offset:26624
	v_or_b32_e32 v17, 0x300, v3
	v_lshlrev_b32_e32 v61, 4, v17
	v_and_b32_e32 v61, 0x3200, v61
	v_add_u32_e32 v61, v16, v61
	ds_read_b32 v61, v61
	v_and_or_b32 v17, v17, s3, v19
	v_lshl_or_b32 v17, v17, 1, v0
	s_movk_i32 s3, 0x360
	s_waitcnt lgkmcnt(0)
	v_mul_f32_e32 v62, 0x3fb8aa3b, v61
	v_exp_f32_e32 v62, v62
	s_nop 0
	v_mul_f32_e32 v60, v62, v60
	v_mul_f32_e32 v60, 0x3e3504f3, v60
	v_cvt_pk_bf16_f32 v60, v60, s0
	ds_write_b16 v17, v60 offset:18432
	v_mul_f32_e32 v60, 0xbfb8aa3b, v61
	v_exp_f32_e32 v60, v60
	s_nop 0
	v_mul_f32_e32 v59, v60, v59
	v_cvt_pk_bf16_f32 v59, v59, s0
	ds_write_b16 v17, v59 offset:26624
	v_or_b32_e32 v17, 0x340, v3
	v_lshlrev_b32_e32 v59, 4, v17
	v_and_b32_e32 v59, 0x3600, v59
	v_add_u32_e32 v59, v16, v59
	ds_read_b32 v59, v59
	v_and_or_b32 v17, v17, s3, v19
	v_lshl_or_b32 v17, v17, 1, v0
	s_movk_i32 s3, 0x3a0
	s_waitcnt lgkmcnt(0)
	v_mul_f32_e32 v60, 0x3fb8aa3b, v59
	v_exp_f32_e32 v60, v60
	s_nop 0
	v_mul_f32_e32 v58, v60, v58
	v_mul_f32_e32 v58, 0x3e3504f3, v58
	v_cvt_pk_bf16_f32 v58, v58, s0
	ds_write_b16 v17, v58 offset:18432
	v_mul_f32_e32 v58, 0xbfb8aa3b, v59
	v_exp_f32_e32 v58, v58
	s_nop 0
	v_mul_f32_e32 v57, v58, v57
	v_cvt_pk_bf16_f32 v57, v57, s0
	ds_write_b16 v17, v57 offset:26624
	v_or_b32_e32 v17, 0x380, v3
	v_lshlrev_b32_e32 v57, 4, v17
	v_and_b32_e32 v57, 0x3a00, v57
	v_add_u32_e32 v57, v16, v57
	ds_read_b32 v57, v57
	v_and_or_b32 v17, v17, s3, v19
	v_lshl_or_b32 v17, v17, 1, v0
	v_or_b32_e32 v3, 0x3c0, v3
	s_movk_i32 s3, 0x3e0
	s_waitcnt lgkmcnt(0)
	v_mul_f32_e32 v58, 0x3fb8aa3b, v57
	v_exp_f32_e32 v58, v58
	s_nop 0
	v_mul_f32_e32 v56, v58, v56
	v_mul_f32_e32 v56, 0x3e3504f3, v56
	v_cvt_pk_bf16_f32 v56, v56, s0
	ds_write_b16 v17, v56 offset:18432
	v_mul_f32_e32 v56, 0xbfb8aa3b, v57
	v_exp_f32_e32 v56, v56
	s_nop 0
	v_mul_f32_e32 v55, v56, v55
	v_cvt_pk_bf16_f32 v55, v55, s0
	ds_write_b16 v17, v55 offset:26624
	v_lshlrev_b32_e32 v17, 4, v3
	v_and_b32_e32 v17, 0x3e00, v17
	v_add_u32_e32 v16, v16, v17
	ds_read_b32 v16, v16
	v_lshlrev_b32_e32 v17, 16, v54
	v_and_or_b32 v3, v3, s3, v19
	v_lshl_or_b32 v3, v3, 1, v0
	s_movk_i32 s3, 0x1200
	s_waitcnt lgkmcnt(0)
	v_mul_f32_e32 v54, 0x3fb8aa3b, v16
	v_exp_f32_e32 v54, v54
	v_mul_f32_e32 v16, 0xbfb8aa3b, v16
	v_exp_f32_e32 v16, v16
	v_and_b32_e32 v19, 48, v15
	v_mul_f32_e32 v17, v54, v17
	v_mul_f32_e32 v17, 0x3e3504f3, v17
	v_cvt_pk_bf16_f32 v17, v17, s0
	ds_write_b16 v3, v17 offset:18432
	v_lshlrev_b32_e32 v17, 16, v53
	v_mul_f32_e32 v16, v16, v17
	v_mul_lo_u32 v17, v1, s3
	s_movk_i32 s3, 0x78
	v_cvt_pk_bf16_f32 v16, v16, s0
	v_and_or_b32 v1, v13, s3, v17
	ds_write_b16 v3, v16 offset:26624
	v_mad_u32_u24 v3, v52, s0, v1
	s_waitcnt lgkmcnt(0)
	s_barrier
	ds_write_b64 v3, v[48:49]
	v_lshrrev_b32_e32 v3, 4, v74
	v_mad_u32_u24 v3, v3, s0, v1
	ds_write_b64 v3, v[44:45]
	v_lshrrev_b32_e32 v3, 4, v75
	v_mad_u32_u24 v3, v3, s0, v1
	ds_write_b64 v3, v[40:41]
	v_lshrrev_b32_e32 v3, 4, v76
	v_mad_u32_u24 v3, v3, s0, v1
	ds_write_b64 v3, v[36:37]
	v_lshrrev_b32_e32 v3, 4, v80
	v_mad_u32_u24 v3, v3, s0, v1
	ds_write_b64 v3, v[32:33]
	v_lshrrev_b32_e32 v3, 4, v78
	v_mad_u32_u24 v3, v3, s0, v1
	ds_write_b64 v3, v[28:29]
	v_lshrrev_b32_e32 v3, 4, v73
	v_mad_u32_u24 v3, v3, s0, v1
	ds_write_b64 v3, v[24:25]
	v_lshrrev_b32_e32 v3, 4, v71
	v_mad_u32_u24 v1, v3, s0, v1
	ds_write_b64 v1, v[20:21]
	v_lshlrev_b32_e32 v1, 6, v7
	v_or3_b32 v0, v0, v19, v1
	s_waitcnt lgkmcnt(0)
	s_barrier
	ds_read_b128 v[20:23], v0 offset:18432
	ds_read_b128 v[24:27], v0 offset:26624
	ds_read_b128 v[36:39], v0 offset:19456
	ds_read_b128 v[30:33], v0 offset:27648
	s_waitcnt lgkmcnt(2)
	v_mfma_f32_16x16x32_bf16 v[40:43], v[24:27], v[20:23], 0
	v_lshlrev_b32_e32 v28, 2, v52
	v_cmp_lt_u32_e64 s[38:39], v28, v7
	v_or_b32_e32 v1, 2, v28
	s_waitcnt lgkmcnt(0)
	v_mfma_f32_16x16x32_bf16 v[30:33], v[30:33], v[36:39], 0
	s_nop 2
	v_cndmask_b32_e64 v3, 0, v41, s[38:39]
	v_cmp_le_u32_e64 s[38:39], v1, v7
	v_cmp_gt_u32_e32 vcc, v28, v7
	v_mfma_f32_16x16x32_bf16 v[24:27], v[24:27], v[36:39], 0
	v_cndmask_b32_e64 v1, 0, v42, s[38:39]
	v_or_b32_e32 v29, 3, v28
	v_or_b32_e32 v35, 17, v28
	v_or_b32_e32 v42, 16, v7
	v_cndmask_b32_e64 v0, v40, 0, vcc
	v_cmp_le_u32_e64 s[38:39], v29, v7
	v_or_b32_e32 v40, 18, v28
	v_cndmask_b32_e64 v29, v30, 0, vcc
	v_cmp_le_u32_e32 vcc, v35, v42
	v_bfe_u32 v15, v15, 2, 2
	v_lshlrev_b32_e32 v16, 3, v52
	v_or_b32_e32 v41, 19, v28
	v_cndmask_b32_e32 v30, 0, v31, vcc
	v_cmp_le_u32_e32 vcc, v40, v42
	v_cvt_pk_bf16_f32 v56, v24, v25
	v_or_b32_e32 v24, v28, v15
	v_cndmask_b32_e32 v31, 0, v32, vcc
	v_cmp_le_u32_e32 vcc, v41, v42
	v_mul_u32_u24_e32 v24, 0x90, v24
	v_and_b32_e32 v13, 24, v13
	v_or_b32_e32 v15, v16, v15
	v_cndmask_b32_e64 v34, 0, v43, s[38:39]
	v_cndmask_b32_e32 v32, 0, v33, vcc
	v_add3_u32 v12, v12, v24, v13
	v_mul_u32_u24_e32 v15, 0x90, v15
	v_cvt_pk_bf16_f32 v1, v1, v34
	v_cvt_pk_bf16_f32 v0, v0, v3
	v_mov_b32_e32 v3, v2
	v_cvt_pk_bf16_f32 v57, v26, v27
	v_cvt_pk_bf16_f32 v58, v29, v30
	v_cvt_pk_bf16_f32 v59, v31, v32
	v_add3_u32 v13, v17, v15, v13
	ds_read_b64_tr_b16 v[26:27], v12 offset:37120
	ds_read_b64_tr_b16 v[24:25], v12 offset:34816
	ds_read_b64_tr_b16 v[28:29], v12 offset:34848
	ds_read_b64_tr_b16 v[32:33], v13 offset:576
	ds_read_b64_tr_b16 v[30:31], v13
	ds_read_b64_tr_b16 v[40:41], v13 offset:32
	s_waitcnt lgkmcnt(4)
	v_mfma_f32_16x16x32_bf16 v[42:45], v[24:27], v[0:3], 0
	v_mov_b32_e32 v17, v2
	v_mfma_f32_16x16x32_bf16 v[24:27], v[24:27], v[56:59], 0
	s_waitcnt lgkmcnt(1)
	v_mfma_f32_16x16x32_bf16 v[52:55], v[30:33], v[20:23], v[42:45]
	v_mfma_f32_16x16x32_bf16 v[32:35], v[30:33], v[36:39], v[24:27]
	ds_read_b64_tr_b16 v[30:31], v12 offset:37152
	s_nop 1
	ds_read_b64_tr_b16 v[42:43], v13 offset:608
	s_waitcnt lgkmcnt(1)
	v_mfma_f32_16x16x32_bf16 v[24:27], v[28:31], v[0:3], 0
	s_nop 1
	v_mul_f32_e64 v80, v32, v32
	v_mul_f32_e64 v81, v33, v33
	s_waitcnt lgkmcnt(0)
	v_mfma_f32_16x16x32_bf16 v[48:51], v[40:43], v[20:23], v[24:27]
	v_mfma_f32_16x16x32_bf16 v[24:27], v[28:31], v[56:59], 0
	v_mfma_f32_16x16x32_bf16 v[28:31], v[40:43], v[36:39], v[24:27]
	s_nop 6
	ds_read_b64_tr_b16 v[24:25], v12 offset:34880
	ds_read_b64_tr_b16 v[26:27], v12 offset:37184
	ds_read_b64_tr_b16 v[40:41], v13 offset:64
	ds_read_b64_tr_b16 v[42:43], v13 offset:640
	ds_read_b64_tr_b16 v[60:61], v12 offset:34912
	ds_read_b64_tr_b16 v[62:63], v12 offset:37216
	ds_read_b64_tr_b16 v[64:65], v13 offset:96
	ds_read_b64_tr_b16 v[66:67], v13 offset:672
	v_pk_mul_f32 v[12:13], v[54:55], v[54:55]
	s_waitcnt lgkmcnt(6)
	v_mfma_f32_16x16x32_bf16 v[44:47], v[24:27], v[0:3], 0
	v_mfma_f32_16x16x32_bf16 v[24:27], v[24:27], v[56:59], 0
	s_waitcnt lgkmcnt(4)
	v_mfma_f32_16x16x32_bf16 v[44:47], v[40:43], v[20:23], v[44:47]
	v_mfma_f32_16x16x32_bf16 v[24:27], v[40:43], v[36:39], v[24:27]
	s_waitcnt lgkmcnt(2)
	v_mfma_f32_16x16x32_bf16 v[40:43], v[60:63], v[0:3], 0
	v_or_b32_e32 v0, s2, v7
	s_waitcnt lgkmcnt(0)
	v_mfma_f32_16x16x32_bf16 v[40:43], v[64:67], v[20:23], v[40:43]
	v_mfma_f32_16x16x32_bf16 v[20:23], v[60:63], v[56:59], 0
	v_mfma_f32_16x16x32_bf16 v[20:23], v[64:67], v[36:39], v[20:23]
	v_mul_f32_e64 v36, v52, v52
	v_mul_f32_e64 v37, v53, v53
	s_nop 3
	v_mul_f32_e32 v1, v40, v40
	v_pk_mov_b32 v[38:39], v[36:37], v[12:13] op_sel:[1,0]
	v_mov_b32_e32 v37, v13
	v_pk_add_f32 v[12:13], v[38:39], v[36:37]
	v_pk_mul_f32 v[36:37], v[50:51], v[50:51]
	v_pk_mul_f32 v[38:39], v[48:49], v[48:49]
	v_mul_f32_e32 v3, v41, v41
	v_pk_mov_b32 v[56:57], v[38:39], v[36:37] op_sel:[1,0]
	v_mov_b32_e32 v39, v37
	v_pk_add_f32 v[36:37], v[56:57], v[38:39]
	v_pk_add_f32 v[12:13], v[12:13], v[12:13] op_sel:[0,1] op_sel_hi:[1,0]
	v_pk_add_f32 v[36:37], v[36:37], v[36:37] op_sel:[0,1] op_sel_hi:[1,0]
	v_mov_b32_e32 v13, v1
	v_mov_b32_e32 v37, v3
	v_pk_add_f32 v[12:13], v[12:13], v[36:37]
	v_mul_f32_e32 v36, v45, v45
	v_mul_f32_e32 v38, v47, v47
	v_mul_f32_e32 v7, v42, v42
	v_mul_f32_e32 v15, v43, v43
	v_pk_fma_f32 v[36:37], v[44:45], v[44:45], v[36:37] op_sel_hi:[1,1,0]
	v_pk_fma_f32 v[38:39], v[46:47], v[46:47], v[38:39] op_sel_hi:[1,1,0]
	v_mov_b32_e32 v37, v7
	v_mov_b32_e32 v39, v15
	v_pk_add_f32 v[36:37], v[36:37], v[38:39]
	s_nop 0
	v_pk_add_f32 v[12:13], v[12:13], v[36:37]
	v_mad_i64_i32 v[36:37], s[2:3], v0, s93, v[4:5]
	v_lshl_add_u64 v[58:59], v[36:37], 0, v[8:9]
	v_lshl_add_u64 v[58:59], v[58:59], 0, v[16:17]
	v_lshl_add_u64 v[74:75], v[58:59], 0, s[8:9]
	v_add_co_u32_e32 v58, vcc, s94, v58
	v_mov_b64_e32 v[68:69], v[138:139]
	v_mov_b64_e32 v[72:73], v[140:141]
	v_addc_co_u32_e32 v59, vcc, 0, v59, vcc
	v_mov_b64_e32 v[62:63], v[136:137]
	v_pk_add_f32 v[12:13], v[12:13], v[12:13] op_sel:[0,1] op_sel_hi:[1,0]
	s_nop 0
	v_and_b32_e32 v3, 0xffff0000, v62
	v_mov_b32_e32 v1, v12
	s_nop 1
	v_permlane16_swap_b32_e32 v12, v1
	v_add_f32_e32 v13, v12, v1
	v_ashrrev_i32_e32 v1, 31, v0
	v_lshlrev_b64 v[36:37], 11, v[0:1]
	v_lshlrev_b32_e32 v1, 16, v62
	v_mul_f32_e32 v7, 0xbfb8aa3b, v1
	v_exp_f32_e32 v58, v7
	v_mul_f32_e32 v7, 0xbfb8aa3b, v3
	v_exp_f32_e32 v59, v7
	v_lshl_add_u64 v[36:37], s[24:25], 0, v[36:37]
	v_lshl_add_u64 v[60:61], v[36:37], 0, v[8:9]
	s_nop 1
	v_mov_b64_e32 v[36:37], v[156:157]
	v_mov_b64_e32 v[38:39], v[158:159]
	v_pk_add_f32 v[58:59], v[58:59], 1.0 op_sel_hi:[1,0]
	v_mov_b32_e32 v57, v13
	v_div_scale_f32 v7, s[2:3], v59, v59, v3
	v_rcp_f32_e32 v12, v7
	v_permlane32_swap_b32_e32 v13, v57
	v_or_b32_e32 v0, 16, v0
	v_fma_f32 v15, -v7, v12, 1.0
	v_fmac_f32_e32 v12, v15, v12
	v_div_scale_f32 v15, vcc, v3, v59, v3
	v_mul_f32_e32 v56, v15, v12
	v_fma_f32 v62, -v7, v56, v15
	v_fmac_f32_e32 v56, v62, v12
	v_fma_f32 v7, -v7, v56, v15
	v_div_fmas_f32 v7, v7, v12, v56
	v_div_fixup_f32 v59, v7, v59, v3
	v_div_scale_f32 v3, s[2:3], v58, v58, v1
	v_rcp_f32_e32 v7, v3
	s_nop 0
	v_fma_f32 v12, -v3, v7, 1.0
	v_fmac_f32_e32 v7, v12, v7
	v_div_scale_f32 v12, vcc, v1, v58, v1
	v_mul_f32_e32 v15, v12, v7
	v_fma_f32 v56, -v3, v15, v12
	v_fmac_f32_e32 v15, v56, v7
	v_fma_f32 v3, -v3, v15, v12
	v_div_fmas_f32 v3, v3, v7, v15
	v_div_fixup_f32 v58, v3, v58, v1
	v_lshlrev_b32_e32 v1, 16, v63
	v_and_b32_e32 v3, 0xffff0000, v63
	v_mul_f32_e32 v7, 0xbfb8aa3b, v1
	v_exp_f32_e32 v62, v7
	v_mul_f32_e32 v7, 0xbfb8aa3b, v3
	v_exp_f32_e32 v63, v7
	s_nop 0
	v_pk_add_f32 v[62:63], v[62:63], 1.0 op_sel_hi:[1,0]
	s_nop 0
	v_div_scale_f32 v7, s[2:3], v63, v63, v3
	v_rcp_f32_e32 v12, v7
	s_nop 0
	v_fma_f32 v15, -v7, v12, 1.0
	v_fmac_f32_e32 v12, v15, v12
	v_div_scale_f32 v15, vcc, v3, v63, v3
	v_mul_f32_e32 v56, v15, v12
	v_fma_f32 v64, -v7, v56, v15
	v_fmac_f32_e32 v56, v64, v12
	v_fma_f32 v7, -v7, v56, v15
	v_div_fmas_f32 v7, v7, v12, v56
	v_div_fixup_f32 v63, v7, v63, v3
	v_div_scale_f32 v3, s[2:3], v62, v62, v1
	v_rcp_f32_e32 v7, v3
	v_lshl_add_u64 v[64:65], v[60:61], 0, v[16:17]
	v_lshl_add_u64 v[60:61], v[64:65], 0, s[10:11]
	v_fma_f32 v12, -v3, v7, 1.0
	v_fmac_f32_e32 v7, v12, v7
	v_div_scale_f32 v12, vcc, v1, v62, v1
	v_mul_f32_e32 v15, v12, v7
	v_fma_f32 v56, -v3, v15, v12
	v_fmac_f32_e32 v15, v56, v7
	v_fma_f32 v3, -v3, v15, v12
	v_div_fmas_f32 v3, v3, v7, v15
	v_div_fixup_f32 v62, v3, v62, v1
	v_lshlrev_b32_e32 v1, 16, v68
	v_and_b32_e32 v3, 0xffff0000, v68
	v_mul_f32_e32 v7, 0xbfb8aa3b, v1
	v_exp_f32_e32 v66, v7
	v_mul_f32_e32 v7, 0xbfb8aa3b, v3
	v_exp_f32_e32 v67, v7
	s_nop 0
	v_pk_add_f32 v[66:67], v[66:67], 1.0 op_sel_hi:[1,0]
	s_nop 0
	v_div_scale_f32 v7, s[2:3], v67, v67, v3
	v_rcp_f32_e32 v12, v7
	s_nop 0
	v_fma_f32 v15, -v7, v12, 1.0
	v_fmac_f32_e32 v12, v15, v12
	v_div_scale_f32 v15, vcc, v3, v67, v3
	v_mul_f32_e32 v56, v15, v12
	v_fma_f32 v68, -v7, v56, v15
	v_fmac_f32_e32 v56, v68, v12
	v_fma_f32 v7, -v7, v56, v15
	v_div_fmas_f32 v7, v7, v12, v56
	v_div_fixup_f32 v67, v7, v67, v3
	v_div_scale_f32 v3, s[2:3], v66, v66, v1
	v_rcp_f32_e32 v7, v3
	s_nop 0
	v_fma_f32 v12, -v3, v7, 1.0
	v_fmac_f32_e32 v7, v12, v7
	v_div_scale_f32 v12, vcc, v1, v66, v1
	v_mul_f32_e32 v15, v12, v7
	v_fma_f32 v56, -v3, v15, v12
	v_fmac_f32_e32 v15, v56, v7
	v_fma_f32 v3, -v3, v15, v12
	v_div_fmas_f32 v3, v3, v7, v15
	v_div_fixup_f32 v66, v3, v66, v1
	v_lshlrev_b32_e32 v1, 16, v69
	v_and_b32_e32 v3, 0xffff0000, v69
	v_mul_f32_e32 v7, 0xbfb8aa3b, v1
	v_exp_f32_e32 v68, v7
	v_mul_f32_e32 v7, 0xbfb8aa3b, v3
	v_exp_f32_e32 v69, v7
	s_nop 0
	v_pk_add_f32 v[68:69], v[68:69], 1.0 op_sel_hi:[1,0]
	s_nop 0
	v_div_scale_f32 v7, s[2:3], v69, v69, v3
	v_rcp_f32_e32 v12, v7
	s_nop 0
	v_fma_f32 v15, -v7, v12, 1.0
	v_fmac_f32_e32 v12, v15, v12
	v_div_scale_f32 v15, vcc, v3, v69, v3
	v_mul_f32_e32 v56, v15, v12
	v_fma_f32 v70, -v7, v56, v15
	v_fmac_f32_e32 v56, v70, v12
	v_fma_f32 v7, -v7, v56, v15
	v_div_fmas_f32 v7, v7, v12, v56
	v_div_fixup_f32 v69, v7, v69, v3
	v_div_scale_f32 v3, s[2:3], v68, v68, v1
	v_rcp_f32_e32 v7, v3
	s_nop 0
	v_fma_f32 v12, -v3, v7, 1.0
	v_fmac_f32_e32 v7, v12, v7
	v_div_scale_f32 v12, vcc, v1, v68, v1
	v_mul_f32_e32 v15, v12, v7
	v_fma_f32 v56, -v3, v15, v12
	v_fmac_f32_e32 v15, v56, v7
	v_fma_f32 v3, -v3, v15, v12
	v_div_fmas_f32 v3, v3, v7, v15
	v_div_fixup_f32 v68, v3, v68, v1
	v_lshlrev_b32_e32 v1, 16, v72
	v_and_b32_e32 v3, 0xffff0000, v72
	v_mul_f32_e32 v7, 0xbfb8aa3b, v1
	v_exp_f32_e32 v70, v7
	v_mul_f32_e32 v7, 0xbfb8aa3b, v3
	v_exp_f32_e32 v71, v7
	s_nop 0
	v_pk_add_f32 v[70:71], v[70:71], 1.0 op_sel_hi:[1,0]
	s_nop 0
	v_div_scale_f32 v7, s[2:3], v71, v71, v3
	v_rcp_f32_e32 v12, v7
	s_nop 0
	v_fma_f32 v15, -v7, v12, 1.0
	v_fmac_f32_e32 v12, v15, v12
	v_div_scale_f32 v15, vcc, v3, v71, v3
	v_mul_f32_e32 v56, v15, v12
	v_fma_f32 v72, -v7, v56, v15
	v_fmac_f32_e32 v56, v72, v12
	v_fma_f32 v7, -v7, v56, v15
	v_div_fmas_f32 v7, v7, v12, v56
	v_div_fixup_f32 v71, v7, v71, v3
	v_div_scale_f32 v3, s[2:3], v70, v70, v1
	v_rcp_f32_e32 v7, v3
	s_nop 0
	v_fma_f32 v12, -v3, v7, 1.0
	v_fmac_f32_e32 v7, v12, v7
	v_div_scale_f32 v12, vcc, v1, v70, v1
	v_mul_f32_e32 v15, v12, v7
	v_fma_f32 v56, -v3, v15, v12
	v_fmac_f32_e32 v15, v56, v7
	v_fma_f32 v3, -v3, v15, v12
	v_div_fmas_f32 v3, v3, v7, v15
	v_div_fixup_f32 v70, v3, v70, v1
	v_lshlrev_b32_e32 v1, 16, v73
	v_and_b32_e32 v3, 0xffff0000, v73
	v_mul_f32_e32 v7, 0xbfb8aa3b, v1
	v_exp_f32_e32 v72, v7
	v_mul_f32_e32 v7, 0xbfb8aa3b, v3
	v_exp_f32_e32 v73, v7
	s_nop 0
	v_pk_add_f32 v[72:73], v[72:73], 1.0 op_sel_hi:[1,0]
	s_nop 0
	v_div_scale_f32 v7, s[2:3], v73, v73, v3
	v_rcp_f32_e32 v12, v7
	s_nop 0
	v_fma_f32 v15, -v7, v12, 1.0
	v_fmac_f32_e32 v12, v15, v12
	v_div_scale_f32 v15, vcc, v3, v73, v3
	v_mul_f32_e32 v56, v15, v12
	v_fma_f32 v76, -v7, v56, v15
	v_fmac_f32_e32 v56, v76, v12
	v_mov_b64_e32 v[76:77], v[142:143]
	v_fma_f32 v7, -v7, v56, v15
	v_div_fmas_f32 v7, v7, v12, v56
	v_div_fixup_f32 v73, v7, v73, v3
	v_div_scale_f32 v3, s[2:3], v72, v72, v1
	v_rcp_f32_e32 v7, v3
	s_nop 0
	v_fma_f32 v12, -v3, v7, 1.0
	v_fmac_f32_e32 v7, v12, v7
	v_div_scale_f32 v12, vcc, v1, v72, v1
	v_mul_f32_e32 v15, v12, v7
	v_fma_f32 v56, -v3, v15, v12
	v_fmac_f32_e32 v15, v56, v7
	v_fma_f32 v3, -v3, v15, v12
	v_div_fmas_f32 v3, v3, v7, v15
	v_div_fixup_f32 v72, v3, v72, v1
	s_nop 0
	v_lshlrev_b32_e32 v1, 16, v76
	v_and_b32_e32 v3, 0xffff0000, v76
	v_mul_f32_e32 v7, 0xbfb8aa3b, v1
	v_exp_f32_e32 v74, v7
	v_mul_f32_e32 v7, 0xbfb8aa3b, v3
	v_exp_f32_e32 v75, v7
	s_nop 0
	v_pk_add_f32 v[74:75], v[74:75], 1.0 op_sel_hi:[1,0]
	s_nop 0
	v_div_scale_f32 v7, s[2:3], v75, v75, v3
	v_rcp_f32_e32 v12, v7
	s_nop 0
	v_fma_f32 v15, -v7, v12, 1.0
	v_fmac_f32_e32 v12, v15, v12
	v_div_scale_f32 v15, vcc, v3, v75, v3
	v_mul_f32_e32 v56, v15, v12
	v_fma_f32 v76, -v7, v56, v15
	v_fmac_f32_e32 v56, v76, v12
	v_fma_f32 v7, -v7, v56, v15
	v_div_fmas_f32 v7, v7, v12, v56
	v_div_fixup_f32 v75, v7, v75, v3
	v_div_scale_f32 v3, s[2:3], v74, v74, v1
	v_rcp_f32_e32 v7, v3
	s_nop 0
	v_fma_f32 v12, -v3, v7, 1.0
	v_fmac_f32_e32 v7, v12, v7
	v_div_scale_f32 v12, vcc, v1, v74, v1
	v_mul_f32_e32 v15, v12, v7
	v_fma_f32 v56, -v3, v15, v12
	v_fmac_f32_e32 v15, v56, v7
	v_fma_f32 v3, -v3, v15, v12
	v_div_fmas_f32 v3, v3, v7, v15
	v_div_fixup_f32 v74, v3, v74, v1
	v_lshlrev_b32_e32 v1, 16, v77
	v_and_b32_e32 v3, 0xffff0000, v77
	v_mul_f32_e32 v7, 0xbfb8aa3b, v1
	v_exp_f32_e32 v76, v7
	v_mul_f32_e32 v7, 0xbfb8aa3b, v3
	v_exp_f32_e32 v77, v7
	s_nop 0
	v_pk_add_f32 v[76:77], v[76:77], 1.0 op_sel_hi:[1,0]
	s_nop 0
	v_div_scale_f32 v7, s[2:3], v77, v77, v3
	v_rcp_f32_e32 v12, v7
	s_nop 0
	v_fma_f32 v15, -v7, v12, 1.0
	v_fmac_f32_e32 v12, v15, v12
	v_div_scale_f32 v15, vcc, v3, v77, v3
	v_mul_f32_e32 v56, v15, v12
	v_fma_f32 v78, -v7, v56, v15
	v_fmac_f32_e32 v56, v78, v12
	v_fma_f32 v7, -v7, v56, v15
	v_div_fmas_f32 v7, v7, v12, v56
	v_div_fixup_f32 v77, v7, v77, v3
	v_div_scale_f32 v3, s[2:3], v76, v76, v1
	v_rcp_f32_e32 v7, v3
	v_pk_mul_f32 v[78:79], v[34:35], v[34:35]
	s_mov_b32 s2, 0x3c800000
	v_pk_mov_b32 v[82:83], v[80:81], v[78:79] op_sel:[1,0]
	v_fma_f32 v12, -v3, v7, 1.0
	v_fmac_f32_e32 v7, v12, v7
	v_div_scale_f32 v12, vcc, v1, v76, v1
	v_mul_f32_e32 v15, v12, v7
	v_fma_f32 v56, -v3, v15, v12
	v_mov_b32_e32 v81, v79
	v_fmac_f32_e32 v15, v56, v7
	v_pk_add_f32 v[78:79], v[82:83], v[80:81]
	v_pk_mul_f32 v[80:81], v[30:31], v[30:31]
	v_pk_mul_f32 v[82:83], v[28:29], v[28:29]
	v_fma_f32 v3, -v3, v15, v12
	v_pk_mov_b32 v[84:85], v[82:83], v[80:81] op_sel:[1,0]
	v_mov_b32_e32 v83, v81
	v_div_fmas_f32 v3, v3, v7, v15
	v_pk_add_f32 v[80:81], v[84:85], v[82:83]
	v_div_fixup_f32 v76, v3, v76, v1
	v_mul_f32_e32 v1, v20, v20
	v_mul_f32_e32 v3, v21, v21
	v_pk_add_f32 v[78:79], v[78:79], v[78:79] op_sel:[0,1] op_sel_hi:[1,0]
	v_pk_add_f32 v[80:81], v[80:81], v[80:81] op_sel:[0,1] op_sel_hi:[1,0]
	v_mov_b32_e32 v79, v1
	v_mov_b32_e32 v81, v3
	v_mul_f32_e32 v12, v25, v25
	v_pk_add_f32 v[78:79], v[78:79], v[80:81]
	v_pk_fma_f32 v[80:81], v[24:25], v[24:25], v[12:13] op_sel_hi:[1,1,0]
	v_mul_f32_e32 v12, v27, v27
	v_mul_f32_e32 v7, v22, v22
	v_mul_f32_e32 v15, v23, v23
	v_pk_fma_f32 v[82:83], v[26:27], v[26:27], v[12:13] op_sel_hi:[1,1,0]
	v_mov_b32_e32 v81, v7
	v_mov_b32_e32 v83, v15
	v_pk_add_f32 v[80:81], v[80:81], v[82:83]
	s_nop 0
	v_pk_add_f32 v[78:79], v[78:79], v[80:81]
	s_nop 0
	v_pk_add_f32 v[78:79], v[78:79], v[78:79] op_sel:[0,1] op_sel_hi:[1,0]
	s_nop 0
	v_mov_b32_e32 v1, v78
	s_nop 1
	v_permlane16_swap_b32_e32 v78, v1
	v_add_f32_e32 v12, v78, v1
	v_mov_b32_e32 v56, v12
	s_nop 1
	v_permlane32_swap_b32_e32 v12, v56
	v_pk_add_f32 v[12:13], v[12:13], v[56:57]
	s_nop 0
	v_pk_fma_f32 v[12:13], v[12:13], s[2:3], v[196:197] op_sel_hi:[1,0,0]
	v_mad_i64_i32 v[4:5], s[2:3], v0, s93, v[4:5]
	v_mul_f32_e32 v1, 0x4b800000, v13
	v_cmp_gt_f32_e64 s[38:39], s22, v13
	v_cmp_gt_f32_e32 vcc, s22, v12
	v_lshl_add_u64 v[4:5], v[4:5], 0, v[8:9]
	v_cndmask_b32_e64 v1, v13, v1, s[38:39]
	v_rsq_f32_e32 v1, v1
	v_lshl_add_u64 v[4:5], v[4:5], 0, v[16:17]
	v_mul_f32_e32 v3, 0x45800000, v1
	v_cndmask_b32_e64 v56, v1, v3, s[38:39]
	v_pk_mul_f32 v[52:53], v[52:53], v[56:57] op_sel_hi:[1,0]
	v_pk_mul_f32 v[48:49], v[48:49], v[56:57] op_sel_hi:[1,0]
	v_pk_mul_f32 v[36:37], v[36:37], v[52:53]
	v_pk_mul_f32 v[52:53], v[54:55], v[56:57] op_sel_hi:[1,0]
	v_pk_mul_f32 v[36:37], v[58:59], v[36:37]
	v_pk_mul_f32 v[38:39], v[38:39], v[52:53]
	v_cvt_pk_bf16_f32 v36, v36, v37
	v_pk_mul_f32 v[38:39], v[62:63], v[38:39]
	v_pk_mul_f32 v[44:45], v[44:45], v[56:57] op_sel_hi:[1,0]
	v_cvt_pk_bf16_f32 v37, v38, v39
	v_add_co_u32_e64 v38, s[38:39], s27, v64
	v_mul_f32_e32 v1, 0x4b800000, v12
	s_nop 0
	v_addc_co_u32_e64 v39, s[38:39], 0, v65, s[38:39]
	global_store_dwordx2 v[38:39], v[36:37], off offset:1536
	s_nop 1
	v_mov_b64_e32 v[36:37], v[160:161]
	v_mov_b64_e32 v[38:39], v[162:163]
	v_cndmask_b32_e32 v1, v12, v1, vcc
	v_rsq_f32_e32 v1, v1
	v_pk_mul_f32 v[40:41], v[40:41], v[56:57] op_sel_hi:[1,0]
	v_mul_f32_e32 v3, 0x45800000, v1
	v_cndmask_b32_e32 v12, v1, v3, vcc
	v_ashrrev_i32_e32 v1, 31, v0
	v_lshlrev_b64 v[0:1], 11, v[0:1]
	v_lshl_add_u64 v[0:1], s[24:25], 0, v[0:1]
	v_lshl_add_u64 v[0:1], v[0:1], 0, v[8:9]
	v_lshl_add_u64 v[8:9], v[4:5], 0, s[8:9]
	v_add_co_u32_e32 v4, vcc, s94, v4
	v_pk_mul_f32 v[32:33], v[32:33], v[12:13] op_sel_hi:[1,0]
	s_nop 0
	v_addc_co_u32_e32 v5, vcc, 0, v5, vcc
	v_mov_b64_e32 v[4:5], v[144:145]
	v_lshl_add_u64 v[0:1], v[0:1], 0, v[16:17]
	v_lshl_add_u64 v[16:17], v[0:1], 0, s[10:11]
	s_nop 0
	v_pk_mul_f32 v[36:37], v[36:37], v[48:49]
	v_pk_mul_f32 v[48:49], v[50:51], v[56:57] op_sel_hi:[1,0]
	v_pk_mul_f32 v[36:37], v[36:37], v[66:67]
	v_pk_mul_f32 v[38:39], v[38:39], v[48:49]
	v_cvt_pk_bf16_f32 v36, v36, v37
	v_pk_mul_f32 v[38:39], v[38:39], v[68:69]
	s_nop 0
	v_lshlrev_b32_e32 v3, 16, v4
	v_cvt_pk_bf16_f32 v37, v38, v39
	global_store_dwordx2 v[60:61], v[36:37], off offset:32
	s_nop 1
	v_mov_b64_e32 v[36:37], v[164:165]
	v_mov_b64_e32 v[38:39], v[166:167]
	v_and_b32_e32 v4, 0xffff0000, v4
	v_mul_f32_e32 v7, 0xbfb8aa3b, v3
	s_nop 0
	v_pk_mul_f32 v[36:37], v[36:37], v[44:45]
	v_pk_mul_f32 v[44:45], v[46:47], v[56:57] op_sel_hi:[1,0]
	v_pk_mul_f32 v[36:37], v[36:37], v[70:71]
	v_pk_mul_f32 v[38:39], v[38:39], v[44:45]
	v_cvt_pk_bf16_f32 v36, v36, v37
	v_pk_mul_f32 v[38:39], v[38:39], v[72:73]
	s_nop 0
	v_cvt_pk_bf16_f32 v37, v38, v39
	global_store_dwordx2 v[60:61], v[36:37], off offset:64
	s_nop 1
	v_mov_b64_e32 v[36:37], v[168:169]
	v_mov_b64_e32 v[38:39], v[170:171]
	s_nop 0
	v_pk_mul_f32 v[36:37], v[36:37], v[40:41]
	v_pk_mul_f32 v[40:41], v[42:43], v[56:57] op_sel_hi:[1,0]
	v_pk_mul_f32 v[36:37], v[36:37], v[74:75]
	v_pk_mul_f32 v[38:39], v[38:39], v[40:41]
	v_cvt_pk_bf16_f32 v36, v36, v37
	v_pk_mul_f32 v[38:39], v[38:39], v[76:77]
	v_exp_f32_e32 v40, v7
	v_cvt_pk_bf16_f32 v37, v38, v39
	global_store_dwordx2 v[60:61], v[36:37], off offset:96
	s_nop 1
	v_mov_b64_e32 v[36:37], v[156:157]
	v_mov_b64_e32 v[38:39], v[158:159]
	v_mul_f32_e32 v7, 0xbfb8aa3b, v4
	v_exp_f32_e32 v41, v7
	s_nop 0
	v_pk_mul_f32 v[32:33], v[36:37], v[32:33]
	v_pk_add_f32 v[36:37], v[40:41], 1.0 op_sel_hi:[1,0]
	s_nop 0
	v_div_scale_f32 v7, s[2:3], v37, v37, v4
	v_rcp_f32_e32 v13, v7
	s_nop 0
	v_fma_f32 v15, -v7, v13, 1.0
	v_fmac_f32_e32 v13, v15, v13
	v_div_scale_f32 v15, vcc, v4, v37, v4
	v_mul_f32_e32 v40, v15, v13
	v_fma_f32 v41, -v7, v40, v15
	v_fmac_f32_e32 v40, v41, v13
	v_fma_f32 v7, -v7, v40, v15
	v_div_fmas_f32 v7, v7, v13, v40
	v_div_fixup_f32 v37, v7, v37, v4
	v_div_scale_f32 v4, s[2:3], v36, v36, v3
	v_rcp_f32_e32 v7, v4
	s_nop 0
	v_fma_f32 v13, -v4, v7, 1.0
	v_fmac_f32_e32 v7, v13, v7
	v_div_scale_f32 v13, vcc, v3, v36, v3
	v_mul_f32_e32 v15, v13, v7
	v_fma_f32 v40, -v4, v15, v13
	v_fmac_f32_e32 v15, v40, v7
	v_fma_f32 v4, -v4, v15, v13
	v_div_fmas_f32 v4, v4, v7, v15
	v_div_fixup_f32 v36, v4, v36, v3
	v_lshlrev_b32_e32 v3, 16, v5
	v_pk_mul_f32 v[32:33], v[36:37], v[32:33]
	v_and_b32_e32 v5, 0xffff0000, v5
	v_mul_f32_e32 v7, 0xbfb8aa3b, v3
	v_cvt_pk_bf16_f32 v4, v32, v33
	v_exp_f32_e32 v32, v7
	v_mul_f32_e32 v7, 0xbfb8aa3b, v5
	v_exp_f32_e32 v33, v7
	v_pk_mul_f32 v[34:35], v[34:35], v[12:13] op_sel_hi:[1,0]
	v_pk_add_f32 v[32:33], v[32:33], 1.0 op_sel_hi:[1,0]
	s_nop 0
	v_div_scale_f32 v7, s[2:3], v33, v33, v5
	v_rcp_f32_e32 v13, v7
	v_pk_mul_f32 v[34:35], v[38:39], v[34:35]
	v_fma_f32 v15, -v7, v13, 1.0
	v_fmac_f32_e32 v13, v15, v13
	v_div_scale_f32 v15, vcc, v5, v33, v5
	v_mul_f32_e32 v36, v15, v13
	v_fma_f32 v37, -v7, v36, v15
	v_fmac_f32_e32 v36, v37, v13
	v_fma_f32 v7, -v7, v36, v15
	v_div_fmas_f32 v7, v7, v13, v36
	v_div_fixup_f32 v33, v7, v33, v5
	v_div_scale_f32 v5, s[2:3], v32, v32, v3
	v_rcp_f32_e32 v7, v5
	s_nop 0
	v_fma_f32 v13, -v5, v7, 1.0
	v_fmac_f32_e32 v7, v13, v7
	v_div_scale_f32 v13, vcc, v3, v32, v3
	v_mul_f32_e32 v15, v13, v7
	v_fma_f32 v36, -v5, v15, v13
	v_fmac_f32_e32 v15, v36, v7
	v_fma_f32 v5, -v5, v15, v13
	v_div_fmas_f32 v5, v5, v7, v15
	v_div_fixup_f32 v32, v5, v32, v3
	v_pk_mul_f32 v[32:33], v[32:33], v[34:35]
	v_add_co_u32_e32 v0, vcc, s27, v0
	v_cvt_pk_bf16_f32 v5, v32, v33
	s_nop 0
	v_addc_co_u32_e32 v1, vcc, 0, v1, vcc
	global_store_dwordx2 v[0:1], v[4:5], off offset:1536
	s_nop 1
	v_mov_b64_e32 v[32:33], v[160:161]
	v_mov_b64_e32 v[34:35], v[162:163]
	s_nop 0
	v_mov_b64_e32 v[0:1], v[146:147]
	v_pk_mul_f32 v[28:29], v[28:29], v[12:13] op_sel_hi:[1,0]
	s_nop 0
	v_lshlrev_b32_e32 v3, 16, v0
	v_and_b32_e32 v0, 0xffff0000, v0
	v_mul_f32_e32 v4, 0xbfb8aa3b, v3
	v_mul_f32_e32 v5, 0xbfb8aa3b, v0
	v_exp_f32_e32 v4, v4
	v_exp_f32_e32 v5, v5
	v_pk_mul_f32 v[28:29], v[32:33], v[28:29]
	v_pk_add_f32 v[4:5], v[4:5], 1.0 op_sel_hi:[1,0]
	s_nop 0
	v_div_scale_f32 v7, s[2:3], v5, v5, v0
	v_rcp_f32_e32 v13, v7
	s_nop 0
	v_fma_f32 v15, -v7, v13, 1.0
	v_fmac_f32_e32 v13, v15, v13
	v_div_scale_f32 v15, vcc, v0, v5, v0
	v_mul_f32_e32 v32, v15, v13
	v_fma_f32 v33, -v7, v32, v15
	v_fmac_f32_e32 v32, v33, v13
	v_fma_f32 v7, -v7, v32, v15
	v_div_fmas_f32 v7, v7, v13, v32
	v_div_fixup_f32 v5, v7, v5, v0
	v_div_scale_f32 v0, s[2:3], v4, v4, v3
	v_rcp_f32_e32 v7, v0
	s_nop 0
	v_fma_f32 v13, -v0, v7, 1.0
	v_fmac_f32_e32 v7, v13, v7
	v_div_scale_f32 v13, vcc, v3, v4, v3
	v_mul_f32_e32 v15, v13, v7
	v_fma_f32 v32, -v0, v15, v13
	v_fmac_f32_e32 v15, v32, v7
	v_fma_f32 v0, -v0, v15, v13
	v_div_fmas_f32 v0, v0, v7, v15
	v_div_fixup_f32 v4, v0, v4, v3
	v_pk_mul_f32 v[4:5], v[28:29], v[4:5]
	v_lshlrev_b32_e32 v3, 16, v1
	v_and_b32_e32 v1, 0xffff0000, v1
	v_cvt_pk_bf16_f32 v0, v4, v5
	v_mul_f32_e32 v4, 0xbfb8aa3b, v3
	v_mul_f32_e32 v5, 0xbfb8aa3b, v1
	v_exp_f32_e32 v4, v4
	v_exp_f32_e32 v5, v5
	v_pk_mul_f32 v[28:29], v[30:31], v[12:13] op_sel_hi:[1,0]
	v_pk_add_f32 v[4:5], v[4:5], 1.0 op_sel_hi:[1,0]
	s_nop 0
	v_div_scale_f32 v7, s[2:3], v5, v5, v1
	v_rcp_f32_e32 v13, v7
	v_pk_mul_f32 v[28:29], v[34:35], v[28:29]
	v_fma_f32 v15, -v7, v13, 1.0
	v_fmac_f32_e32 v13, v15, v13
	v_div_scale_f32 v15, vcc, v1, v5, v1
	v_mul_f32_e32 v30, v15, v13
	v_fma_f32 v31, -v7, v30, v15
	v_fmac_f32_e32 v30, v31, v13
	v_fma_f32 v7, -v7, v30, v15
	v_div_fmas_f32 v7, v7, v13, v30
	v_div_fixup_f32 v5, v7, v5, v1
	v_div_scale_f32 v1, s[2:3], v4, v4, v3
	v_rcp_f32_e32 v7, v1
	s_nop 0
	v_fma_f32 v13, -v1, v7, 1.0
	v_fmac_f32_e32 v7, v13, v7
	v_div_scale_f32 v13, vcc, v3, v4, v3
	v_mul_f32_e32 v15, v13, v7
	v_fma_f32 v30, -v1, v15, v13
	v_fmac_f32_e32 v15, v30, v7
	v_fma_f32 v1, -v1, v15, v13
	v_div_fmas_f32 v1, v1, v7, v15
	v_div_fixup_f32 v4, v1, v4, v3
	v_pk_mul_f32 v[4:5], v[28:29], v[4:5]
	v_pk_mul_f32 v[24:25], v[24:25], v[12:13] op_sel_hi:[1,0]
	v_cvt_pk_bf16_f32 v1, v4, v5
	global_store_dwordx2 v[16:17], v[0:1], off offset:32
	s_nop 1
	v_mov_b64_e32 v[28:29], v[164:165]
	v_mov_b64_e32 v[30:31], v[166:167]
	s_nop 0
	v_mov_b64_e32 v[0:1], v[148:149]
	s_nop 0
	v_pk_mul_f32 v[24:25], v[28:29], v[24:25]
	s_nop 0
	v_lshlrev_b32_e32 v3, 16, v0
	v_and_b32_e32 v0, 0xffff0000, v0
	v_mul_f32_e32 v4, 0xbfb8aa3b, v3
	v_mul_f32_e32 v5, 0xbfb8aa3b, v0
	v_exp_f32_e32 v4, v4
	v_exp_f32_e32 v5, v5
	s_nop 0
	v_pk_add_f32 v[4:5], v[4:5], 1.0 op_sel_hi:[1,0]
	s_nop 0
	v_div_scale_f32 v7, s[2:3], v5, v5, v0
	v_rcp_f32_e32 v13, v7
	s_nop 0
	v_fma_f32 v15, -v7, v13, 1.0
	v_fmac_f32_e32 v13, v15, v13
	v_div_scale_f32 v15, vcc, v0, v5, v0
	v_mul_f32_e32 v28, v15, v13
	v_fma_f32 v29, -v7, v28, v15
	v_fmac_f32_e32 v28, v29, v13
	v_fma_f32 v7, -v7, v28, v15
	v_div_fmas_f32 v7, v7, v13, v28
	v_div_fixup_f32 v5, v7, v5, v0
	v_div_scale_f32 v0, s[2:3], v4, v4, v3
	v_rcp_f32_e32 v7, v0
	s_nop 0
	v_fma_f32 v13, -v0, v7, 1.0
	v_fmac_f32_e32 v7, v13, v7
	v_div_scale_f32 v13, vcc, v3, v4, v3
	v_mul_f32_e32 v15, v13, v7
	v_fma_f32 v28, -v0, v15, v13
	v_fmac_f32_e32 v15, v28, v7
	v_fma_f32 v0, -v0, v15, v13
	v_div_fmas_f32 v0, v0, v7, v15
	v_div_fixup_f32 v4, v0, v4, v3
	v_pk_mul_f32 v[4:5], v[24:25], v[4:5]
	v_lshlrev_b32_e32 v3, 16, v1
	v_and_b32_e32 v1, 0xffff0000, v1
	v_cvt_pk_bf16_f32 v0, v4, v5
	v_mul_f32_e32 v4, 0xbfb8aa3b, v3
	v_mul_f32_e32 v5, 0xbfb8aa3b, v1
	v_exp_f32_e32 v4, v4
	v_exp_f32_e32 v5, v5
	v_pk_mul_f32 v[24:25], v[26:27], v[12:13] op_sel_hi:[1,0]
	v_pk_add_f32 v[4:5], v[4:5], 1.0 op_sel_hi:[1,0]
	s_nop 0
	v_div_scale_f32 v7, s[2:3], v5, v5, v1
	v_rcp_f32_e32 v13, v7
	v_pk_mul_f32 v[24:25], v[30:31], v[24:25]
	v_fma_f32 v15, -v7, v13, 1.0
	v_fmac_f32_e32 v13, v15, v13
	v_div_scale_f32 v15, vcc, v1, v5, v1
	v_mul_f32_e32 v26, v15, v13
	v_fma_f32 v27, -v7, v26, v15
	v_fmac_f32_e32 v26, v27, v13
	v_fma_f32 v7, -v7, v26, v15
	v_div_fmas_f32 v7, v7, v13, v26
	v_div_fixup_f32 v5, v7, v5, v1
	v_div_scale_f32 v1, s[2:3], v4, v4, v3
	v_rcp_f32_e32 v7, v1
	s_nop 0
	v_fma_f32 v13, -v1, v7, 1.0
	v_fmac_f32_e32 v7, v13, v7
	v_div_scale_f32 v13, vcc, v3, v4, v3
	v_mul_f32_e32 v15, v13, v7
	v_fma_f32 v26, -v1, v15, v13
	v_fmac_f32_e32 v15, v26, v7
	v_fma_f32 v1, -v1, v15, v13
	v_div_fmas_f32 v1, v1, v7, v15
	v_div_fixup_f32 v4, v1, v4, v3
	v_pk_mul_f32 v[4:5], v[24:25], v[4:5]
	s_nop 0
	v_cvt_pk_bf16_f32 v1, v4, v5
	global_store_dwordx2 v[16:17], v[0:1], off offset:64
	s_nop 1
	v_mov_b64_e32 v[24:25], v[168:169]
	v_mov_b64_e32 v[26:27], v[170:171]
	s_nop 0
	v_mov_b64_e32 v[0:1], v[150:151]
	v_pk_mul_f32 v[8:9], v[20:21], v[12:13] op_sel_hi:[1,0]
	s_nop 0
	v_lshlrev_b32_e32 v3, 16, v0
	v_and_b32_e32 v0, 0xffff0000, v0
	v_mul_f32_e32 v4, 0xbfb8aa3b, v3
	v_mul_f32_e32 v5, 0xbfb8aa3b, v0
	v_exp_f32_e32 v4, v4
	v_exp_f32_e32 v5, v5
	v_pk_mul_f32 v[8:9], v[24:25], v[8:9]
	v_pk_add_f32 v[4:5], v[4:5], 1.0 op_sel_hi:[1,0]
	s_nop 0
	v_div_scale_f32 v7, s[2:3], v5, v5, v0
	v_rcp_f32_e32 v13, v7
	s_nop 0
	v_fma_f32 v15, -v7, v13, 1.0
	v_fmac_f32_e32 v13, v15, v13
	v_div_scale_f32 v15, vcc, v0, v5, v0
	v_mul_f32_e32 v19, v15, v13
	v_fma_f32 v20, -v7, v19, v15
	v_fmac_f32_e32 v19, v20, v13
	v_fma_f32 v7, -v7, v19, v15
	v_div_fmas_f32 v7, v7, v13, v19
	v_div_fixup_f32 v5, v7, v5, v0
	v_div_scale_f32 v0, s[2:3], v4, v4, v3
	v_rcp_f32_e32 v7, v0
	s_nop 0
	v_fma_f32 v13, -v0, v7, 1.0
	v_fmac_f32_e32 v7, v13, v7
	v_div_scale_f32 v13, vcc, v3, v4, v3
	v_mul_f32_e32 v15, v13, v7
	v_fma_f32 v19, -v0, v15, v13
	v_fmac_f32_e32 v15, v19, v7
	v_fma_f32 v0, -v0, v15, v13
	v_div_fmas_f32 v0, v0, v7, v15
	v_div_fixup_f32 v4, v0, v4, v3
	v_pk_mul_f32 v[4:5], v[8:9], v[4:5]
	v_lshlrev_b32_e32 v3, 16, v1
	v_and_b32_e32 v1, 0xffff0000, v1
	v_cvt_pk_bf16_f32 v0, v4, v5
	v_mul_f32_e32 v4, 0xbfb8aa3b, v3
	v_mul_f32_e32 v5, 0xbfb8aa3b, v1
	v_exp_f32_e32 v4, v4
	v_exp_f32_e32 v5, v5
	v_pk_mul_f32 v[8:9], v[22:23], v[12:13] op_sel_hi:[1,0]
	v_pk_add_f32 v[4:5], v[4:5], 1.0 op_sel_hi:[1,0]
	s_nop 0
	v_div_scale_f32 v7, s[2:3], v5, v5, v1
	v_rcp_f32_e32 v12, v7
	v_pk_mul_f32 v[8:9], v[26:27], v[8:9]
	v_fma_f32 v13, -v7, v12, 1.0
	v_fmac_f32_e32 v12, v13, v12
	v_div_scale_f32 v13, vcc, v1, v5, v1
	v_mul_f32_e32 v15, v13, v12
	v_fma_f32 v19, -v7, v15, v13
	v_fmac_f32_e32 v15, v19, v12
	v_fma_f32 v7, -v7, v15, v13
	v_div_fmas_f32 v7, v7, v12, v15
	v_div_fixup_f32 v5, v7, v5, v1
	v_div_scale_f32 v1, s[2:3], v4, v4, v3
	v_rcp_f32_e32 v7, v1
	v_readlane_b32 s2, v248, 4
	s_mov_b32 s38, s2
	v_fma_f32 v12, -v1, v7, 1.0
	v_fmac_f32_e32 v7, v12, v7
	v_div_scale_f32 v12, vcc, v3, v4, v3
	v_mul_f32_e32 v13, v12, v7
	v_fma_f32 v15, -v1, v13, v12
	v_fmac_f32_e32 v13, v15, v7
	v_fma_f32 v1, -v1, v13, v12
	v_div_fmas_f32 v1, v1, v7, v13
	v_div_fixup_f32 v4, v1, v4, v3
	v_pk_mul_f32 v[4:5], v[8:9], v[4:5]
	s_nop 0
	v_cvt_pk_bf16_f32 v1, v4, v5
	global_store_dwordx2 v[16:17], v[0:1], off offset:96
	s_cbranch_scc1 .LBB0_585
